# batched K-fragment reads also in the B-layer mixer score loops (3 tiles per batch, single buffer)
# baseline (speedup 1.0000x reference)
.LBB0_89:
	s_or_b64 exec, exec, s[4:5]
	v_and_b32_e32 v5, 64, v229
	v_mov_b32_e32 v1, v4
	v_xor_b32_e32 v4, 16, v229
	v_add_u32_e32 v5, 64, v5
	v_cmp_lt_i32_e32 vcc, v4, v5
	v_and_b32_e32 v71, 15, v52
	v_mad_u32_u24 v79, v71, s14, v72
	v_cndmask_b32_e32 v78, v229, v4, vcc
	v_xor_b32_e32 v4, 32, v229
	v_cmp_lt_i32_e32 vcc, v4, v5
	v_mov_b32_e32 v65, v6
	v_cndmask_b32_e32 v73, v229, v4, vcc
	v_lshlrev_b32_e32 v73, 2, v73
	ds_read_b128 v[204:207], v79
	ds_read_b128 v[208:211], v79 offset:64
	ds_read_b128 v[212:215], v79 offset:2304
	ds_read_b128 v[216:219], v79 offset:2368
	ds_read_b128 v[240:243], v79 offset:4608
	ds_read_b128 v[244:247], v79 offset:4672
	s_waitcnt lgkmcnt(0)
	v_mfma_f32_16x16x32_bf16 v[60:63], v[204:207], v[0:3], 0
	v_mfma_f32_16x16x32_bf16 v[56:59], v[212:215], v[0:3], 0
	v_mfma_f32_16x16x32_bf16 v[52:55], v[240:243], v[0:3], 0
	v_mfma_f32_16x16x32_bf16 v[60:63], v[208:211], v[64:67], v[60:63]
	v_mfma_f32_16x16x32_bf16 v[56:59], v[216:219], v[64:67], v[56:59]
	v_mfma_f32_16x16x32_bf16 v[52:55], v[244:247], v[64:67], v[52:55]
	ds_read_b128 v[204:207], v79 offset:6912
	ds_read_b128 v[208:211], v79 offset:6976
	ds_read_b128 v[212:215], v79 offset:9216
	ds_read_b128 v[216:219], v79 offset:9280
	ds_read_b128 v[240:243], v79 offset:11520
	ds_read_b128 v[244:247], v79 offset:11584
	s_waitcnt lgkmcnt(0)
	v_mfma_f32_16x16x32_bf16 v[48:51], v[204:207], v[0:3], 0
	v_mfma_f32_16x16x32_bf16 v[44:47], v[212:215], v[0:3], 0
	v_mfma_f32_16x16x32_bf16 v[40:43], v[240:243], v[0:3], 0
	v_mfma_f32_16x16x32_bf16 v[48:51], v[208:211], v[64:67], v[48:51]
	v_mfma_f32_16x16x32_bf16 v[44:47], v[216:219], v[64:67], v[44:47]
	v_mfma_f32_16x16x32_bf16 v[40:43], v[244:247], v[64:67], v[40:43]
	ds_read_b128 v[204:207], v79 offset:13824
	ds_read_b128 v[208:211], v79 offset:13888
	ds_read_b128 v[212:215], v79 offset:16128
	ds_read_b128 v[216:219], v79 offset:16192
	ds_read_b128 v[240:243], v79 offset:18432
	ds_read_b128 v[244:247], v79 offset:18496
	s_waitcnt lgkmcnt(0)
	v_mfma_f32_16x16x32_bf16 v[36:39], v[204:207], v[0:3], 0
	v_mfma_f32_16x16x32_bf16 v[32:35], v[212:215], v[0:3], 0
	v_mfma_f32_16x16x32_bf16 v[28:31], v[240:243], v[0:3], 0
	v_mfma_f32_16x16x32_bf16 v[36:39], v[208:211], v[64:67], v[36:39]
	v_mfma_f32_16x16x32_bf16 v[32:35], v[216:219], v[64:67], v[32:35]
	v_mfma_f32_16x16x32_bf16 v[28:31], v[244:247], v[64:67], v[28:31]
	ds_read_b128 v[204:207], v79 offset:20736
	ds_read_b128 v[208:211], v79 offset:20800
	ds_read_b128 v[212:215], v79 offset:23040
	ds_read_b128 v[216:219], v79 offset:23104
	ds_read_b128 v[240:243], v79 offset:25344
	ds_read_b128 v[244:247], v79 offset:25408
	s_waitcnt lgkmcnt(0)
	v_mfma_f32_16x16x32_bf16 v[24:27], v[204:207], v[0:3], 0
	v_mfma_f32_16x16x32_bf16 v[20:23], v[212:215], v[0:3], 0
	v_mfma_f32_16x16x32_bf16 v[16:19], v[240:243], v[0:3], 0
	v_mfma_f32_16x16x32_bf16 v[24:27], v[208:211], v[64:67], v[24:27]
	v_mfma_f32_16x16x32_bf16 v[20:23], v[216:219], v[64:67], v[20:23]
	v_mfma_f32_16x16x32_bf16 v[16:19], v[244:247], v[64:67], v[16:19]
	ds_read_b128 v[204:207], v79 offset:27648
	ds_read_b128 v[208:211], v79 offset:27712
	ds_read_b128 v[212:215], v79 offset:29952
	ds_read_b128 v[216:219], v79 offset:30016
	ds_read_b128 v[240:243], v79 offset:32256
	ds_read_b128 v[244:247], v79 offset:32320
	s_waitcnt lgkmcnt(0)
	v_mfma_f32_16x16x32_bf16 v[12:15], v[204:207], v[0:3], 0
	v_mfma_f32_16x16x32_bf16 v[8:11], v[212:215], v[0:3], 0
	v_mfma_f32_16x16x32_bf16 v[4:7], v[240:243], v[0:3], 0
	v_mfma_f32_16x16x32_bf16 v[12:15], v[208:211], v[64:67], v[12:15]
	v_mfma_f32_16x16x32_bf16 v[8:11], v[216:219], v[64:67], v[8:11]
	v_mfma_f32_16x16x32_bf16 v[4:7], v[244:247], v[64:67], v[4:7]
	ds_read_b128 v[204:207], v79 offset:34560
	ds_read_b128 v[208:211], v79 offset:34624
	s_waitcnt lgkmcnt(0)
	v_mfma_f32_16x16x32_bf16 v[212:215], v[204:207], v[0:3], 0
	v_mfma_f32_16x16x32_bf16 v[0:3], v[208:211], v[64:67], v[212:215]
	v_mul_f32_e32 v64, 0x3e000000, v60
	v_mul_f32_e32 v65, 0x3e000000, v61
	s_mov_b32 s2, 0xff61b1e6
	v_max3_f32 v64, v64, s2, v65
	v_mul_f32_e32 v65, 0x3e000000, v62
	v_mul_f32_e32 v66, 0x3e000000, v63
	v_max3_f32 v64, v64, v65, v66
	v_mul_f32_e32 v65, 0x3e000000, v56
	v_mul_f32_e32 v66, 0x3e000000, v57
	v_max3_f32 v64, v64, v65, v66
	v_mul_f32_e32 v65, 0x3e000000, v58
	v_mul_f32_e32 v66, 0x3e000000, v59
	v_max3_f32 v64, v64, v65, v66
	v_mul_f32_e32 v65, 0x3e000000, v52
	v_mul_f32_e32 v66, 0x3e000000, v53
	v_max3_f32 v64, v64, v65, v66
	v_mul_f32_e32 v65, 0x3e000000, v54
	v_mul_f32_e32 v66, 0x3e000000, v55
	v_max3_f32 v64, v64, v65, v66
	v_mul_f32_e32 v65, 0x3e000000, v48
	v_mul_f32_e32 v66, 0x3e000000, v49
	v_max3_f32 v64, v64, v65, v66
	v_mul_f32_e32 v65, 0x3e000000, v50
	v_mul_f32_e32 v66, 0x3e000000, v51
	v_max3_f32 v64, v64, v65, v66
	v_mul_f32_e32 v65, 0x3e000000, v44
	v_mul_f32_e32 v66, 0x3e000000, v45
	v_max3_f32 v64, v64, v65, v66
	v_mul_f32_e32 v65, 0x3e000000, v46
	v_mul_f32_e32 v66, 0x3e000000, v47
	v_max3_f32 v64, v64, v65, v66
	v_mul_f32_e32 v65, 0x3e000000, v40
	v_mul_f32_e32 v66, 0x3e000000, v41
	v_max3_f32 v64, v64, v65, v66
	v_mul_f32_e32 v65, 0x3e000000, v42
	v_mul_f32_e32 v66, 0x3e000000, v43
	v_max3_f32 v64, v64, v65, v66
	v_mul_f32_e32 v65, 0x3e000000, v36
	v_mul_f32_e32 v66, 0x3e000000, v37
	v_max3_f32 v64, v64, v65, v66
	v_mul_f32_e32 v65, 0x3e000000, v38
	v_mul_f32_e32 v66, 0x3e000000, v39
	v_max3_f32 v64, v64, v65, v66
	v_mul_f32_e32 v65, 0x3e000000, v32
	v_mul_f32_e32 v66, 0x3e000000, v33
	v_max3_f32 v64, v64, v65, v66
	v_mul_f32_e32 v65, 0x3e000000, v34
	v_mul_f32_e32 v66, 0x3e000000, v35
	v_max3_f32 v64, v64, v65, v66
	v_mul_f32_e32 v65, 0x3e000000, v28
	v_mul_f32_e32 v66, 0x3e000000, v29
	v_max3_f32 v64, v64, v65, v66
	v_mul_f32_e32 v65, 0x3e000000, v30
	v_mul_f32_e32 v66, 0x3e000000, v31
	v_max3_f32 v64, v64, v65, v66
	v_mul_f32_e32 v65, 0x3e000000, v24
	v_mul_f32_e32 v66, 0x3e000000, v25
	v_max3_f32 v64, v64, v65, v66
	v_mul_f32_e32 v65, 0x3e000000, v26
	v_mul_f32_e32 v66, 0x3e000000, v27
	v_max3_f32 v64, v64, v65, v66
	v_mul_f32_e32 v65, 0x3e000000, v20
	v_mul_f32_e32 v66, 0x3e000000, v21
	v_max3_f32 v64, v64, v65, v66
	v_mul_f32_e32 v65, 0x3e000000, v22
	v_mul_f32_e32 v66, 0x3e000000, v23
	v_max3_f32 v64, v64, v65, v66
	v_mul_f32_e32 v65, 0x3e000000, v16
	v_mul_f32_e32 v66, 0x3e000000, v17
	v_max3_f32 v64, v64, v65, v66
	v_mul_f32_e32 v65, 0x3e000000, v18
	v_mul_f32_e32 v66, 0x3e000000, v19
	v_max3_f32 v64, v64, v65, v66
	v_mul_f32_e32 v65, 0x3e000000, v12
	v_mul_f32_e32 v66, 0x3e000000, v13
	v_max3_f32 v64, v64, v65, v66
	v_mul_f32_e32 v65, 0x3e000000, v14
	v_mul_f32_e32 v66, 0x3e000000, v15
	v_max3_f32 v64, v64, v65, v66
	v_mul_f32_e32 v65, 0x3e000000, v8
	v_mul_f32_e32 v66, 0x3e000000, v9
	v_max3_f32 v64, v64, v65, v66
	v_mul_f32_e32 v65, 0x3e000000, v10
	v_mul_f32_e32 v66, 0x3e000000, v11
	v_max3_f32 v64, v64, v65, v66
	v_mul_f32_e32 v65, 0x3e000000, v4
	v_mul_f32_e32 v66, 0x3e000000, v5
	v_max3_f32 v64, v64, v65, v66
	v_mul_f32_e32 v65, 0x3e000000, v6
	v_mul_f32_e32 v66, 0x3e000000, v7
	v_max3_f32 v64, v64, v65, v66
	v_mul_f32_e32 v65, 0x3e000000, v0
	v_mul_f32_e32 v66, 0x3e000000, v1
	v_max3_f32 v64, v64, v65, v66
	v_mul_f32_e32 v65, 0x3e000000, v2
	v_mul_f32_e32 v66, 0x3e000000, v3
	v_max3_f32 v64, v64, v65, v66
	v_lshlrev_b32_e32 v74, 2, v78
	ds_bpermute_b32 v65, v74, v64
	s_mov_b32 s2, 0x3e000000
	v_sub_u32_e32 v72, v72, v70
	s_waitcnt lgkmcnt(0)
	v_max_f32_e32 v65, v65, v65
	v_max_f32_e32 v64, v64, v65
	ds_bpermute_b32 v65, v73, v64
	s_waitcnt lgkmcnt(0)
	v_max_f32_e32 v65, v65, v65
	v_max_f32_e32 v75, v64, v65
	v_fma_f32 v60, v60, s2, -v75
	v_fma_f32 v61, v61, s2, -v75
	v_mul_f32_e32 v60, 0x3fb8aa3b, v60
	v_mul_f32_e32 v61, 0x3fb8aa3b, v61
	v_exp_f32_e32 v60, v60
	v_exp_f32_e32 v64, v61
	v_fma_f32 v61, v62, s2, -v75
	v_mul_f32_e32 v61, 0x3fb8aa3b, v61
	v_exp_f32_e32 v61, v61
	v_add_f32_e32 v65, 0, v60
	v_fma_f32 v63, v63, s2, -v75
	v_add_f32_e32 v65, v64, v65
	v_mul_f32_e32 v63, 0x3fb8aa3b, v63
	v_add_f32_e32 v62, v61, v65
	v_exp_f32_e32 v65, v63
	v_fma_f32 v56, v56, s2, -v75
	v_mul_f32_e32 v56, 0x3fb8aa3b, v56
	v_fma_f32 v57, v57, s2, -v75
	v_add_f32_e32 v63, v65, v62
	v_exp_f32_e32 v62, v56
	v_mul_f32_e32 v57, 0x3fb8aa3b, v57
	v_exp_f32_e32 v66, v57
	v_fma_f32 v57, v58, s2, -v75
	v_mul_f32_e32 v57, 0x3fb8aa3b, v57
	v_add_f32_e32 v56, v62, v63
	v_exp_f32_e32 v63, v57
	v_fma_f32 v57, v59, s2, -v75
	v_mul_f32_e32 v57, 0x3fb8aa3b, v57
	v_fma_f32 v52, v52, s2, -v75
	v_exp_f32_e32 v67, v57
	v_mul_f32_e32 v52, 0x3fb8aa3b, v52
	v_exp_f32_e32 v52, v52
	v_add_f32_e32 v56, v66, v56
	v_add_f32_e32 v56, v63, v56
	v_fma_f32 v53, v53, s2, -v75
	v_add_f32_e32 v56, v67, v56
	v_mul_f32_e32 v53, 0x3fb8aa3b, v53
	v_add_f32_e32 v57, v52, v56
	v_exp_f32_e32 v56, v53
	v_fma_f32 v53, v54, s2, -v75
	v_mul_f32_e32 v53, 0x3fb8aa3b, v53
	v_exp_f32_e32 v53, v53
	v_fma_f32 v55, v55, s2, -v75
	v_add_f32_e32 v57, v56, v57
	v_mul_f32_e32 v55, 0x3fb8aa3b, v55
	v_add_f32_e32 v54, v53, v57
	v_exp_f32_e32 v57, v55
	v_fma_f32 v48, v48, s2, -v75
	v_mul_f32_e32 v48, 0x3fb8aa3b, v48
	v_fma_f32 v49, v49, s2, -v75
	v_add_f32_e32 v55, v57, v54
	v_exp_f32_e32 v54, v48
	v_mul_f32_e32 v49, 0x3fb8aa3b, v49
	v_exp_f32_e32 v58, v49
	v_fma_f32 v49, v50, s2, -v75
	v_mul_f32_e32 v49, 0x3fb8aa3b, v49
	v_add_f32_e32 v48, v54, v55
	v_exp_f32_e32 v55, v49
	v_fma_f32 v49, v51, s2, -v75
	v_mul_f32_e32 v49, 0x3fb8aa3b, v49
	v_fma_f32 v44, v44, s2, -v75
	v_exp_f32_e32 v59, v49
	v_mul_f32_e32 v44, 0x3fb8aa3b, v44
	v_exp_f32_e32 v44, v44
	v_add_f32_e32 v48, v58, v48
	v_add_f32_e32 v48, v55, v48
	v_fma_f32 v45, v45, s2, -v75
	v_add_f32_e32 v48, v59, v48
	v_mul_f32_e32 v45, 0x3fb8aa3b, v45
	v_add_f32_e32 v49, v44, v48
	v_exp_f32_e32 v48, v45
	v_fma_f32 v45, v46, s2, -v75
	v_mul_f32_e32 v45, 0x3fb8aa3b, v45
	v_exp_f32_e32 v45, v45
	v_fma_f32 v47, v47, s2, -v75
	v_add_f32_e32 v49, v48, v49
	v_mul_f32_e32 v47, 0x3fb8aa3b, v47
	v_add_f32_e32 v46, v45, v49
	v_exp_f32_e32 v49, v47
	v_fma_f32 v40, v40, s2, -v75
	v_mul_f32_e32 v40, 0x3fb8aa3b, v40
	v_fma_f32 v41, v41, s2, -v75
	v_add_f32_e32 v47, v49, v46
	v_exp_f32_e32 v46, v40
	v_mul_f32_e32 v41, 0x3fb8aa3b, v41
	v_exp_f32_e32 v50, v41
	v_fma_f32 v41, v42, s2, -v75
	v_mul_f32_e32 v41, 0x3fb8aa3b, v41
	v_add_f32_e32 v40, v46, v47
	v_exp_f32_e32 v47, v41
	v_fma_f32 v41, v43, s2, -v75
	v_mul_f32_e32 v41, 0x3fb8aa3b, v41
	v_fma_f32 v36, v36, s2, -v75
	v_exp_f32_e32 v51, v41
	v_mul_f32_e32 v36, 0x3fb8aa3b, v36
	v_exp_f32_e32 v36, v36
	v_add_f32_e32 v40, v50, v40
	v_add_f32_e32 v40, v47, v40
	v_fma_f32 v37, v37, s2, -v75
	v_add_f32_e32 v40, v51, v40
	v_mul_f32_e32 v37, 0x3fb8aa3b, v37
	v_add_f32_e32 v41, v36, v40
	v_exp_f32_e32 v40, v37
	v_fma_f32 v37, v38, s2, -v75
	v_mul_f32_e32 v37, 0x3fb8aa3b, v37
	v_exp_f32_e32 v37, v37
	v_fma_f32 v39, v39, s2, -v75
	v_add_f32_e32 v41, v40, v41
	v_mul_f32_e32 v39, 0x3fb8aa3b, v39
	v_add_f32_e32 v38, v37, v41
	v_exp_f32_e32 v41, v39
	v_fma_f32 v32, v32, s2, -v75
	v_mul_f32_e32 v32, 0x3fb8aa3b, v32
	v_fma_f32 v33, v33, s2, -v75
	v_add_f32_e32 v39, v41, v38
	v_exp_f32_e32 v38, v32
	v_mul_f32_e32 v33, 0x3fb8aa3b, v33
	v_exp_f32_e32 v42, v33
	v_fma_f32 v33, v34, s2, -v75
	v_mul_f32_e32 v33, 0x3fb8aa3b, v33
	v_add_f32_e32 v32, v38, v39
	v_exp_f32_e32 v39, v33
	v_fma_f32 v33, v35, s2, -v75
	v_mul_f32_e32 v33, 0x3fb8aa3b, v33
	v_fma_f32 v28, v28, s2, -v75
	v_exp_f32_e32 v43, v33
	v_mul_f32_e32 v28, 0x3fb8aa3b, v28
	v_exp_f32_e32 v28, v28
	v_add_f32_e32 v32, v42, v32
	v_add_f32_e32 v32, v39, v32
	v_fma_f32 v29, v29, s2, -v75
	v_add_f32_e32 v32, v43, v32
	v_mul_f32_e32 v29, 0x3fb8aa3b, v29
	v_add_f32_e32 v33, v28, v32
	v_exp_f32_e32 v32, v29
	v_fma_f32 v29, v30, s2, -v75
	v_mul_f32_e32 v29, 0x3fb8aa3b, v29
	v_exp_f32_e32 v29, v29
	v_fma_f32 v31, v31, s2, -v75
	v_add_f32_e32 v33, v32, v33
	v_mul_f32_e32 v31, 0x3fb8aa3b, v31
	v_add_f32_e32 v30, v29, v33
	v_exp_f32_e32 v33, v31
	v_fma_f32 v24, v24, s2, -v75
	v_mul_f32_e32 v24, 0x3fb8aa3b, v24
	v_fma_f32 v25, v25, s2, -v75
	v_add_f32_e32 v31, v33, v30
	v_exp_f32_e32 v30, v24
	v_mul_f32_e32 v25, 0x3fb8aa3b, v25
	v_exp_f32_e32 v34, v25
	v_fma_f32 v25, v26, s2, -v75
	v_mul_f32_e32 v25, 0x3fb8aa3b, v25
	v_add_f32_e32 v24, v30, v31
	v_exp_f32_e32 v31, v25
	v_fma_f32 v25, v27, s2, -v75
	v_mul_f32_e32 v25, 0x3fb8aa3b, v25
	v_fma_f32 v20, v20, s2, -v75
	v_exp_f32_e32 v35, v25
	v_mul_f32_e32 v20, 0x3fb8aa3b, v20
	v_exp_f32_e32 v20, v20
	v_add_f32_e32 v24, v34, v24
	v_add_f32_e32 v24, v31, v24
	v_fma_f32 v21, v21, s2, -v75
	v_add_f32_e32 v24, v35, v24
	v_mul_f32_e32 v21, 0x3fb8aa3b, v21
	v_add_f32_e32 v25, v20, v24
	v_exp_f32_e32 v24, v21
	v_fma_f32 v21, v22, s2, -v75
	v_mul_f32_e32 v21, 0x3fb8aa3b, v21
	v_exp_f32_e32 v21, v21
	v_fma_f32 v23, v23, s2, -v75
	v_add_f32_e32 v25, v24, v25
	v_mul_f32_e32 v23, 0x3fb8aa3b, v23
	v_add_f32_e32 v22, v21, v25
	v_exp_f32_e32 v25, v23
	v_fma_f32 v16, v16, s2, -v75
	v_mul_f32_e32 v16, 0x3fb8aa3b, v16
	v_fma_f32 v17, v17, s2, -v75
	v_add_f32_e32 v23, v25, v22
	v_exp_f32_e32 v22, v16
	v_mul_f32_e32 v17, 0x3fb8aa3b, v17
	v_exp_f32_e32 v26, v17
	v_fma_f32 v17, v18, s2, -v75
	v_mul_f32_e32 v17, 0x3fb8aa3b, v17
	v_add_f32_e32 v16, v22, v23
	v_exp_f32_e32 v23, v17
	v_fma_f32 v17, v19, s2, -v75
	v_mul_f32_e32 v17, 0x3fb8aa3b, v17
	v_fma_f32 v12, v12, s2, -v75
	v_exp_f32_e32 v27, v17
	v_mul_f32_e32 v12, 0x3fb8aa3b, v12
	v_exp_f32_e32 v12, v12
	v_add_f32_e32 v16, v26, v16
	v_add_f32_e32 v16, v23, v16
	v_fma_f32 v13, v13, s2, -v75
	v_add_f32_e32 v16, v27, v16
	v_mul_f32_e32 v13, 0x3fb8aa3b, v13
	v_add_f32_e32 v17, v12, v16
	v_exp_f32_e32 v16, v13
	v_fma_f32 v13, v14, s2, -v75
	v_mul_f32_e32 v13, 0x3fb8aa3b, v13
	v_exp_f32_e32 v13, v13
	v_fma_f32 v15, v15, s2, -v75
	v_add_f32_e32 v17, v16, v17
	v_mul_f32_e32 v15, 0x3fb8aa3b, v15
	v_add_f32_e32 v14, v13, v17
	v_exp_f32_e32 v17, v15
	v_fma_f32 v8, v8, s2, -v75
	v_mul_f32_e32 v8, 0x3fb8aa3b, v8
	v_fma_f32 v9, v9, s2, -v75
	v_add_f32_e32 v15, v17, v14
	v_exp_f32_e32 v14, v8
	v_mul_f32_e32 v9, 0x3fb8aa3b, v9
	v_exp_f32_e32 v18, v9
	v_fma_f32 v9, v10, s2, -v75
	v_mul_f32_e32 v9, 0x3fb8aa3b, v9
	v_add_f32_e32 v8, v14, v15
	v_exp_f32_e32 v15, v9
	v_fma_f32 v9, v11, s2, -v75
	v_mul_f32_e32 v9, 0x3fb8aa3b, v9
	v_fma_f32 v4, v4, s2, -v75
	v_exp_f32_e32 v19, v9
	v_mul_f32_e32 v4, 0x3fb8aa3b, v4
	v_exp_f32_e32 v4, v4
	v_add_f32_e32 v8, v18, v8
	v_add_f32_e32 v8, v15, v8
	v_fma_f32 v5, v5, s2, -v75
	v_add_f32_e32 v8, v19, v8
	v_mul_f32_e32 v5, 0x3fb8aa3b, v5
	v_add_f32_e32 v9, v4, v8
	v_exp_f32_e32 v8, v5
	v_fma_f32 v5, v6, s2, -v75
	v_mul_f32_e32 v5, 0x3fb8aa3b, v5
	v_exp_f32_e32 v5, v5
	v_fma_f32 v7, v7, s2, -v75
	v_add_f32_e32 v9, v8, v9
	v_mul_f32_e32 v7, 0x3fb8aa3b, v7
	v_fma_f32 v0, v0, s2, -v75
	v_add_f32_e32 v6, v5, v9
	v_exp_f32_e32 v9, v7
	v_mul_f32_e32 v0, 0x3fb8aa3b, v0
	v_exp_f32_e32 v0, v0
	v_fma_f32 v1, v1, s2, -v75
	v_add_f32_e32 v6, v9, v6
	v_mul_f32_e32 v1, 0x3fb8aa3b, v1
	v_add_f32_e32 v7, v0, v6
	v_exp_f32_e32 v6, v1
	v_fma_f32 v1, v2, s2, -v75
	v_mul_f32_e32 v1, 0x3fb8aa3b, v1
	v_exp_f32_e32 v1, v1
	v_fma_f32 v3, v3, s2, -v75
	v_add_f32_e32 v7, v6, v7
	v_mul_f32_e32 v3, 0x3fb8aa3b, v3
	v_add_f32_e32 v2, v1, v7
	v_exp_f32_e32 v7, v3
	s_nop 0
	v_add_f32_e32 v2, v7, v2
	ds_bpermute_b32 v3, v74, v2
	s_waitcnt lgkmcnt(0)
	v_add_f32_e32 v2, v2, v3
	ds_bpermute_b32 v3, v73, v2
	s_waitcnt lgkmcnt(0)
	v_add_f32_e32 v2, v2, v3
	v_div_scale_f32 v3, s[2:3], v2, v2, 1.0
	v_rcp_f32_e32 v10, v3
	v_div_scale_f32 v11, vcc, 1.0, v2, 1.0
	s_movk_i32 s2, 0x210
	v_fma_f32 v73, -v3, v10, 1.0
	v_fmac_f32_e32 v10, v73, v10
	v_mul_f32_e32 v73, v11, v10
	v_fma_f32 v74, -v3, v73, v11
	v_fmac_f32_e32 v73, v74, v10
	v_fma_f32 v3, -v3, v73, v11
	v_div_fmas_f32 v3, v3, v10, v73
	v_div_fixup_f32 v2, v3, v2, 1.0
	v_pk_mul_f32 v[10:11], v[60:61], v[2:3] op_sel_hi:[1,0]
	v_pk_mul_f32 v[60:61], v[64:65], v[2:3] op_sel_hi:[1,0]
	v_pk_mul_f32 v[64:65], v[66:67], v[2:3] op_sel_hi:[1,0]
	v_pk_mul_f32 v[62:63], v[62:63], v[2:3] op_sel_hi:[1,0]
	v_bfe_u32 v3, v65, 16, 1
	v_bfe_u32 v66, v64, 16, 1
	v_bfe_u32 v67, v61, 16, 1
	v_bfe_u32 v73, v60, 16, 1
	v_add3_u32 v65, v65, v3, s33
	v_bfe_u32 v3, v10, 16, 1
	v_mad_u32_u24 v71, v71, s2, v72
	v_add3_u32 v73, v60, v73, s33
	v_add3_u32 v74, v61, v67, s33
	v_add3_u32 v64, v64, v66, s33
	v_bfe_u32 v60, v11, 16, 1
	v_bfe_u32 v61, v62, 16, 1
	v_bfe_u32 v66, v63, 16, 1
	v_add3_u32 v10, v10, v3, s33
	v_add_u32_e32 v3, 0x9000, v71
	v_add3_u32 v66, v63, v66, s33
	v_add3_u32 v67, v62, v61, s33
	v_add3_u32 v11, v11, v60, s33
	ds_read2_b64 v[60:63], v3 offset1:4
	v_lshrrev_b32_e32 v10, 16, v10
	v_lshrrev_b32_e32 v11, 16, v11
	v_lshrrev_b32_e32 v72, 16, v67
	v_lshrrev_b32_e32 v66, 16, v66
	v_and_or_b32 v67, v65, s29, v66
	v_and_or_b32 v66, v64, s29, v72
	v_and_or_b32 v65, v74, s29, v11
	v_and_or_b32 v64, v73, s29, v10
	v_add_u32_e32 v10, 0xb000, v71
	s_waitcnt lgkmcnt(0)
	v_mfma_f32_16x16x32_bf16 v[72:75], v[60:63], v[64:67], 0
	ds_read2_b64 v[60:63], v10 offset0:32 offset1:36
	s_waitcnt lgkmcnt(0)
	v_mfma_f32_16x16x32_bf16 v[76:79], v[60:63], v[64:67], 0
	v_add_u32_e32 v60, 0xd000, v71
	v_add_u32_e32 v61, 0xf000, v71
	ds_read2_b64 v[82:85], v60 offset0:64 offset1:68
	ds_read2_b64 v[86:89], v61 offset0:96 offset1:100
	s_waitcnt lgkmcnt(1)
	v_mfma_f32_16x16x32_bf16 v[82:85], v[82:85], v[64:67], 0
	s_waitcnt lgkmcnt(0)
	v_mfma_f32_16x16x32_bf16 v[62:65], v[86:89], v[64:67], 0
	v_mul_f32_e64 v56, v56, v2
	v_mul_f32_e64 v57, v57, v2
	v_pk_mul_f32 v[58:59], v[58:59], v[2:3] op_sel_hi:[1,0]
	v_pk_mul_f32 v[52:53], v[52:53], v[2:3] op_sel_hi:[1,0]
	v_pk_mul_f32 v[54:55], v[54:55], v[2:3] op_sel_hi:[1,0]
	v_bfe_u32 v11, v59, 16, 1
	v_bfe_u32 v66, v58, 16, 1
	v_bfe_u32 v67, v57, 16, 1
	v_bfe_u32 v71, v56, 16, 1
	v_add3_u32 v56, v56, v71, s33
	v_add3_u32 v57, v57, v67, s33
	v_add3_u32 v58, v58, v66, s33
	v_add3_u32 v11, v59, v11, s33
	v_bfe_u32 v59, v52, 16, 1
	v_bfe_u32 v66, v53, 16, 1
	v_bfe_u32 v67, v54, 16, 1
	v_bfe_u32 v71, v55, 16, 1
	v_add3_u32 v71, v55, v71, s33
	v_add3_u32 v67, v54, v67, s33
	v_add3_u32 v66, v53, v66, s33
	v_add3_u32 v59, v52, v59, s33
	ds_read2_b64 v[52:55], v3 offset0:8 offset1:12
	v_lshrrev_b32_e32 v81, 16, v59
	v_lshrrev_b32_e32 v66, 16, v66
	v_lshrrev_b32_e32 v67, 16, v67
	v_lshrrev_b32_e32 v59, 16, v71
	v_and_or_b32 v59, v11, s29, v59
	v_and_or_b32 v58, v58, s29, v67
	v_and_or_b32 v57, v57, s29, v66
	v_and_or_b32 v56, v56, s29, v81
	s_waitcnt lgkmcnt(0)
	s_nop 0
	v_mfma_f32_16x16x32_bf16 v[52:55], v[52:55], v[56:59], v[72:75]
	s_nop 2
	ds_read2_b64 v[72:75], v10 offset0:40 offset1:44
	s_waitcnt lgkmcnt(0)
	v_mfma_f32_16x16x32_bf16 v[72:75], v[72:75], v[56:59], v[76:79]
	s_nop 2
	ds_read2_b64 v[76:79], v60 offset0:72 offset1:76
	s_waitcnt lgkmcnt(0)
	v_mfma_f32_16x16x32_bf16 v[76:79], v[76:79], v[56:59], v[82:85]
	s_nop 2
	ds_read2_b64 v[82:85], v61 offset0:104 offset1:108
	s_waitcnt lgkmcnt(0)
	v_mfma_f32_16x16x32_bf16 v[56:59], v[82:85], v[56:59], v[62:65]
	v_mul_f32_e64 v48, v48, v2
	v_mul_f32_e64 v49, v49, v2
	v_pk_mul_f32 v[50:51], v[50:51], v[2:3] op_sel_hi:[1,0]
	v_pk_mul_f32 v[44:45], v[44:45], v[2:3] op_sel_hi:[1,0]
	v_pk_mul_f32 v[46:47], v[46:47], v[2:3] op_sel_hi:[1,0]
	v_bfe_u32 v11, v51, 16, 1
	v_bfe_u32 v62, v50, 16, 1
	v_bfe_u32 v63, v49, 16, 1
	v_bfe_u32 v64, v48, 16, 1
	v_add3_u32 v48, v48, v64, s33
	v_add3_u32 v49, v49, v63, s33
	v_add3_u32 v50, v50, v62, s33
	v_add3_u32 v11, v51, v11, s33
	v_bfe_u32 v51, v44, 16, 1
	v_bfe_u32 v62, v45, 16, 1
	v_bfe_u32 v63, v46, 16, 1
	v_bfe_u32 v64, v47, 16, 1
	v_add3_u32 v64, v47, v64, s33
	v_add3_u32 v63, v46, v63, s33
	v_add3_u32 v62, v45, v62, s33
	v_add3_u32 v51, v44, v51, s33
	ds_read2_b64 v[44:47], v3 offset0:16 offset1:20
	v_lshrrev_b32_e32 v65, 16, v51
	v_lshrrev_b32_e32 v62, 16, v62
	v_lshrrev_b32_e32 v63, 16, v63
	v_lshrrev_b32_e32 v51, 16, v64
	v_and_or_b32 v51, v11, s29, v51
	v_and_or_b32 v50, v50, s29, v63
	v_and_or_b32 v49, v49, s29, v62
	v_and_or_b32 v48, v48, s29, v65
	ds_read2_b64 v[62:65], v60 offset0:80 offset1:84
	s_waitcnt lgkmcnt(1)
	v_mfma_f32_16x16x32_bf16 v[44:47], v[44:47], v[48:51], v[52:55]
	s_nop 2
	ds_read2_b64 v[52:55], v10 offset0:48 offset1:52
	s_waitcnt lgkmcnt(0)
	v_mfma_f32_16x16x32_bf16 v[52:55], v[52:55], v[48:51], v[72:75]
	s_nop 2
	ds_read2_b64 v[72:75], v61 offset0:112 offset1:116
	v_mfma_f32_16x16x32_bf16 v[62:65], v[62:65], v[48:51], v[76:79]
	s_waitcnt lgkmcnt(0)
	v_mfma_f32_16x16x32_bf16 v[48:51], v[72:75], v[48:51], v[56:59]
	v_mul_f32_e64 v40, v40, v2
	v_mul_f32_e64 v41, v41, v2
	v_pk_mul_f32 v[42:43], v[42:43], v[2:3] op_sel_hi:[1,0]
	v_pk_mul_f32 v[36:37], v[36:37], v[2:3] op_sel_hi:[1,0]
	v_pk_mul_f32 v[38:39], v[38:39], v[2:3] op_sel_hi:[1,0]
	v_bfe_u32 v11, v43, 16, 1
	v_bfe_u32 v56, v42, 16, 1
	v_bfe_u32 v57, v41, 16, 1
	v_bfe_u32 v58, v40, 16, 1
	v_add3_u32 v40, v40, v58, s33
	v_add3_u32 v41, v41, v57, s33
	v_add3_u32 v42, v42, v56, s33
	v_add3_u32 v11, v43, v11, s33
	v_bfe_u32 v43, v36, 16, 1
	v_bfe_u32 v56, v37, 16, 1
	v_bfe_u32 v57, v38, 16, 1
	v_bfe_u32 v58, v39, 16, 1
	v_add3_u32 v58, v39, v58, s33
	v_add3_u32 v57, v38, v57, s33
	v_add3_u32 v56, v37, v56, s33
	v_add3_u32 v43, v36, v43, s33
	ds_read2_b64 v[36:39], v3 offset0:24 offset1:28
	v_lshrrev_b32_e32 v59, 16, v43
	v_lshrrev_b32_e32 v56, 16, v56
	v_lshrrev_b32_e32 v57, 16, v57
	v_lshrrev_b32_e32 v43, 16, v58
	v_and_or_b32 v43, v11, s29, v43
	v_and_or_b32 v42, v42, s29, v57
	v_and_or_b32 v41, v41, s29, v56
	v_and_or_b32 v40, v40, s29, v59
	ds_read2_b64 v[56:59], v61 offset0:120 offset1:124
	s_waitcnt lgkmcnt(1)
	v_mfma_f32_16x16x32_bf16 v[36:39], v[36:39], v[40:43], v[44:47]
	s_nop 2
	ds_read2_b64 v[44:47], v10 offset0:56 offset1:60
	s_waitcnt lgkmcnt(0)
	v_mfma_f32_16x16x32_bf16 v[44:47], v[44:47], v[40:43], v[52:55]
	s_nop 2
	ds_read2_b64 v[52:55], v60 offset0:88 offset1:92
	s_waitcnt lgkmcnt(0)
	v_mfma_f32_16x16x32_bf16 v[52:55], v[52:55], v[40:43], v[62:65]
	v_mfma_f32_16x16x32_bf16 v[40:43], v[56:59], v[40:43], v[48:51]
	v_mul_f32_e64 v32, v32, v2
	v_mul_f32_e64 v33, v33, v2
	v_pk_mul_f32 v[34:35], v[34:35], v[2:3] op_sel_hi:[1,0]
	v_pk_mul_f32 v[28:29], v[28:29], v[2:3] op_sel_hi:[1,0]
	v_pk_mul_f32 v[30:31], v[30:31], v[2:3] op_sel_hi:[1,0]
	v_bfe_u32 v11, v35, 16, 1
	v_bfe_u32 v48, v34, 16, 1
	v_bfe_u32 v49, v33, 16, 1
	v_bfe_u32 v50, v32, 16, 1
	v_add3_u32 v32, v32, v50, s33
	v_add3_u32 v33, v33, v49, s33
	v_add3_u32 v34, v34, v48, s33
	v_add3_u32 v11, v35, v11, s33
	v_bfe_u32 v35, v28, 16, 1
	v_bfe_u32 v48, v29, 16, 1
	v_bfe_u32 v49, v30, 16, 1
	v_bfe_u32 v50, v31, 16, 1
	v_add3_u32 v50, v31, v50, s33
	v_add3_u32 v49, v30, v49, s33
	v_add3_u32 v48, v29, v48, s33
	v_add3_u32 v35, v28, v35, s33
	ds_read2_b64 v[28:31], v3 offset0:32 offset1:36
	v_lshrrev_b32_e32 v51, 16, v35
	v_lshrrev_b32_e32 v48, 16, v48
	v_lshrrev_b32_e32 v49, 16, v49
	v_lshrrev_b32_e32 v35, 16, v50
	v_and_or_b32 v35, v11, s29, v35
	v_and_or_b32 v34, v34, s29, v49
	v_and_or_b32 v33, v33, s29, v48
	v_and_or_b32 v32, v32, s29, v51
	ds_read2_b64 v[48:51], v61 offset0:128 offset1:132
	s_waitcnt lgkmcnt(1)
	v_mfma_f32_16x16x32_bf16 v[28:31], v[28:31], v[32:35], v[36:39]
	s_nop 2
	ds_read2_b64 v[36:39], v10 offset0:64 offset1:68
	s_waitcnt lgkmcnt(0)
	v_mfma_f32_16x16x32_bf16 v[36:39], v[36:39], v[32:35], v[44:47]
	s_nop 2
	ds_read2_b64 v[44:47], v60 offset0:96 offset1:100
	s_waitcnt lgkmcnt(0)
	v_mfma_f32_16x16x32_bf16 v[44:47], v[44:47], v[32:35], v[52:55]
	v_mfma_f32_16x16x32_bf16 v[32:35], v[48:51], v[32:35], v[40:43]
	v_mul_f32_e64 v24, v24, v2
	v_mul_f32_e64 v25, v25, v2
	v_pk_mul_f32 v[26:27], v[26:27], v[2:3] op_sel_hi:[1,0]
	v_pk_mul_f32 v[20:21], v[20:21], v[2:3] op_sel_hi:[1,0]
	v_pk_mul_f32 v[22:23], v[22:23], v[2:3] op_sel_hi:[1,0]
	v_bfe_u32 v11, v27, 16, 1
	v_bfe_u32 v40, v26, 16, 1
	v_bfe_u32 v41, v25, 16, 1
	v_bfe_u32 v42, v24, 16, 1
	v_add3_u32 v24, v24, v42, s33
	v_add3_u32 v25, v25, v41, s33
	v_add3_u32 v26, v26, v40, s33
	v_add3_u32 v11, v27, v11, s33
	v_bfe_u32 v27, v20, 16, 1
	v_bfe_u32 v40, v21, 16, 1
	v_bfe_u32 v41, v22, 16, 1
	v_bfe_u32 v42, v23, 16, 1
	v_add3_u32 v42, v23, v42, s33
	v_add3_u32 v41, v22, v41, s33
	v_add3_u32 v40, v21, v40, s33
	v_add3_u32 v27, v20, v27, s33
	ds_read2_b64 v[20:23], v3 offset0:40 offset1:44
	v_lshrrev_b32_e32 v43, 16, v27
	v_lshrrev_b32_e32 v40, 16, v40
	v_lshrrev_b32_e32 v41, 16, v41
	v_lshrrev_b32_e32 v27, 16, v42
	v_and_or_b32 v27, v11, s29, v27
	v_and_or_b32 v26, v26, s29, v41
	v_and_or_b32 v25, v25, s29, v40
	v_and_or_b32 v24, v24, s29, v43
	ds_read2_b64 v[40:43], v61 offset0:136 offset1:140
	s_waitcnt lgkmcnt(1)
	v_mfma_f32_16x16x32_bf16 v[20:23], v[20:23], v[24:27], v[28:31]
	s_nop 2
	ds_read2_b64 v[28:31], v10 offset0:72 offset1:76
	s_waitcnt lgkmcnt(0)
	v_mfma_f32_16x16x32_bf16 v[28:31], v[28:31], v[24:27], v[36:39]
	s_nop 2
	ds_read2_b64 v[36:39], v60 offset0:104 offset1:108
	s_waitcnt lgkmcnt(0)
	v_mfma_f32_16x16x32_bf16 v[36:39], v[36:39], v[24:27], v[44:47]
	v_mfma_f32_16x16x32_bf16 v[24:27], v[40:43], v[24:27], v[32:35]
	v_mul_f32_e64 v16, v16, v2
	v_mul_f32_e64 v17, v17, v2
	v_pk_mul_f32 v[18:19], v[18:19], v[2:3] op_sel_hi:[1,0]
	v_pk_mul_f32 v[12:13], v[12:13], v[2:3] op_sel_hi:[1,0]
	v_pk_mul_f32 v[14:15], v[14:15], v[2:3] op_sel_hi:[1,0]
	v_bfe_u32 v11, v19, 16, 1
	v_bfe_u32 v32, v18, 16, 1
	v_bfe_u32 v33, v17, 16, 1
	v_bfe_u32 v34, v16, 16, 1
	v_add3_u32 v16, v16, v34, s33
	v_add3_u32 v17, v17, v33, s33
	v_add3_u32 v18, v18, v32, s33
	v_add3_u32 v11, v19, v11, s33
	v_bfe_u32 v19, v12, 16, 1
	v_bfe_u32 v32, v13, 16, 1
	v_bfe_u32 v33, v14, 16, 1
	v_bfe_u32 v34, v15, 16, 1
	v_add3_u32 v34, v15, v34, s33
	v_add3_u32 v33, v14, v33, s33
	v_add3_u32 v32, v13, v32, s33
	v_add3_u32 v19, v12, v19, s33
	ds_read2_b64 v[12:15], v3 offset0:48 offset1:52
	v_lshrrev_b32_e32 v35, 16, v19
	v_lshrrev_b32_e32 v32, 16, v32
	v_lshrrev_b32_e32 v33, 16, v33
	v_lshrrev_b32_e32 v19, 16, v34
	v_and_or_b32 v19, v11, s29, v19
	v_and_or_b32 v18, v18, s29, v33
	v_and_or_b32 v17, v17, s29, v32
	v_and_or_b32 v16, v16, s29, v35
	ds_read2_b64 v[32:35], v61 offset0:144 offset1:148
	s_waitcnt lgkmcnt(1)
	v_mfma_f32_16x16x32_bf16 v[12:15], v[12:15], v[16:19], v[20:23]
	s_nop 2
	ds_read2_b64 v[20:23], v10 offset0:80 offset1:84
	s_waitcnt lgkmcnt(0)
	v_mfma_f32_16x16x32_bf16 v[20:23], v[20:23], v[16:19], v[28:31]
	s_nop 2
	ds_read2_b64 v[28:31], v60 offset0:112 offset1:116
	s_waitcnt lgkmcnt(0)
	v_mfma_f32_16x16x32_bf16 v[28:31], v[28:31], v[16:19], v[36:39]
	v_mfma_f32_16x16x32_bf16 v[16:19], v[32:35], v[16:19], v[24:27]
	v_mul_f32_e64 v8, v8, v2
	v_mul_f32_e64 v9, v9, v2
	v_pk_mul_f32 v[6:7], v[6:7], v[2:3] op_sel_hi:[1,0]
	v_pk_mul_f32 v[4:5], v[4:5], v[2:3] op_sel_hi:[1,0]
	v_pk_mul_f32 v[0:1], v[0:1], v[2:3] op_sel_hi:[1,0]
	v_bfe_u32 v2, v7, 16, 1
	v_bfe_u32 v24, v9, 16, 1
	v_bfe_u32 v25, v8, 16, 1
	v_add3_u32 v8, v8, v25, s33
	v_add3_u32 v9, v9, v24, s33
	v_add3_u32 v7, v7, v2, s33
	v_bfe_u32 v2, v4, 16, 1
	v_bfe_u32 v24, v0, 16, 1
	v_bfe_u32 v25, v1, 16, 1
	v_add3_u32 v25, v1, v25, s33
	v_add3_u32 v24, v0, v24, s33
	v_add3_u32 v4, v4, v2, s33
	ds_read2_b64 v[0:3], v3 offset0:56 offset1:60
	v_bfe_u32 v11, v6, 16, 1
	v_add3_u32 v6, v6, v11, s33
	v_bfe_u32 v11, v5, 16, 1
	v_add3_u32 v5, v5, v11, s33
	v_lshrrev_b32_e32 v4, 16, v4
	v_lshrrev_b32_e32 v5, 16, v5
	v_lshrrev_b32_e32 v11, 16, v24
	v_lshrrev_b32_e32 v24, 16, v25
	v_and_or_b32 v27, v7, s29, v24
	v_and_or_b32 v26, v6, s29, v11
	v_and_or_b32 v25, v9, s29, v5
	v_and_or_b32 v24, v8, s29, v4
	s_waitcnt lgkmcnt(0)
	s_nop 0
	v_mfma_f32_16x16x32_bf16 v[12:15], v[0:3], v[24:27], v[12:15]
	ds_read2_b64 v[0:3], v10 offset0:88 offset1:92
	s_waitcnt lgkmcnt(0)
	v_mfma_f32_16x16x32_bf16 v[8:11], v[0:3], v[24:27], v[20:23]
	ds_read2_b64 v[0:3], v60 offset0:120 offset1:124
	s_waitcnt lgkmcnt(0)
	v_mfma_f32_16x16x32_bf16 v[4:7], v[0:3], v[24:27], v[28:31]
	ds_read2_b64 v[0:3], v61 offset0:152 offset1:156
	s_waitcnt lgkmcnt(0)
	v_mfma_f32_16x16x32_bf16 v[0:3], v[0:3], v[24:27], v[16:19]
	s_and_b64 exec, exec, s[0:1]
	s_cbranch_execz .LBB0_91
	s_lshl_b32 s0, s10, 11
	v_bfe_u32 v18, v12, 16, 1
	s_add_u32 s0, s6, s0
	v_add3_u32 v12, v12, v18, s33
	v_bfe_u32 v18, v13, 16, 1
	s_addc_u32 s1, s7, 0
	v_add3_u32 v13, v13, v18, s33
	v_lshrrev_b32_e32 v12, 16, v12
	s_add_u32 s0, s0, s11
	v_and_or_b32 v12, v13, s29, v12
	v_bfe_u32 v13, v14, 16, 1
	s_addc_u32 s1, s1, 0
	v_lshlrev_b64 v[16:17], 11, v[68:69]
	v_add3_u32 v13, v14, v13, s33
	v_bfe_u32 v14, v15, 16, 1
	v_lshl_add_u64 v[16:17], s[0:1], 0, v[16:17]
	v_mov_b32_e32 v71, v80
	v_add3_u32 v14, v15, v14, s33
	v_lshrrev_b32_e32 v13, 16, v13
	v_lshl_add_u64 v[16:17], v[16:17], 0, v[70:71]
	v_and_or_b32 v13, v14, s29, v13
	global_store_dwordx2 v[16:17], v[12:13], off offset:1536
	v_bfe_u32 v12, v8, 16, 1
	v_add3_u32 v8, v8, v12, s33
	v_bfe_u32 v12, v9, 16, 1
	v_add3_u32 v9, v9, v12, s33
	v_lshrrev_b32_e32 v8, 16, v8
	v_and_or_b32 v8, v9, s29, v8
	v_bfe_u32 v9, v10, 16, 1
	v_add3_u32 v9, v10, v9, s33
	v_bfe_u32 v10, v11, 16, 1
	v_add3_u32 v10, v11, v10, s33
	v_lshrrev_b32_e32 v9, 16, v9
	v_and_or_b32 v9, v10, s29, v9
	global_store_dwordx2 v[16:17], v[8:9], off offset:1568
	v_bfe_u32 v8, v4, 16, 1
	v_add3_u32 v4, v4, v8, s33
	v_bfe_u32 v8, v5, 16, 1
	v_add3_u32 v5, v5, v8, s33
	v_lshrrev_b32_e32 v4, 16, v4
	v_and_or_b32 v4, v5, s29, v4
	v_bfe_u32 v5, v6, 16, 1
	v_add3_u32 v5, v6, v5, s33
	v_bfe_u32 v6, v7, 16, 1
	v_add3_u32 v6, v7, v6, s33
	v_lshrrev_b32_e32 v5, 16, v5
	v_and_or_b32 v5, v6, s29, v5
	global_store_dwordx2 v[16:17], v[4:5], off offset:1600
	v_bfe_u32 v4, v0, 16, 1
	v_add3_u32 v0, v0, v4, s33
	v_bfe_u32 v4, v1, 16, 1
	v_add3_u32 v1, v1, v4, s33
	v_lshrrev_b32_e32 v0, 16, v0
	v_and_or_b32 v0, v1, s29, v0
	v_bfe_u32 v1, v2, 16, 1
	v_add3_u32 v1, v2, v1, s33
	v_bfe_u32 v2, v3, 16, 1
	v_add3_u32 v2, v3, v2, s33
	v_lshrrev_b32_e32 v1, 16, v1
	v_and_or_b32 v1, v2, s29, v1
	global_store_dwordx2 v[16:17], v[0:1], off offset:1632

.LBB0_101:
	ds_read_b128 v[204:207], v82
	ds_read_b128 v[208:211], v82 offset:64
	ds_read_b128 v[212:215], v82 offset:2304
	ds_read_b128 v[216:219], v82 offset:2368
	ds_read_b128 v[240:243], v82 offset:4608
	ds_read_b128 v[244:247], v82 offset:4672
	s_waitcnt lgkmcnt(0)
	v_mfma_f32_16x16x32_bf16 v[68:71], v[204:207], v[72:75], 0
	v_mfma_f32_16x16x32_bf16 v[64:67], v[212:215], v[72:75], 0
	v_mfma_f32_16x16x32_bf16 v[60:63], v[240:243], v[72:75], 0
	v_mfma_f32_16x16x32_bf16 v[68:71], v[208:211], v[8:11], v[68:71]
	v_mfma_f32_16x16x32_bf16 v[64:67], v[216:219], v[8:11], v[64:67]
	v_mfma_f32_16x16x32_bf16 v[60:63], v[244:247], v[8:11], v[60:63]
	ds_read_b128 v[204:207], v82 offset:6912
	ds_read_b128 v[208:211], v82 offset:6976
	ds_read_b128 v[212:215], v82 offset:9216
	ds_read_b128 v[216:219], v82 offset:9280
	ds_read_b128 v[240:243], v82 offset:11520
	ds_read_b128 v[244:247], v82 offset:11584
	s_waitcnt lgkmcnt(0)
	v_mfma_f32_16x16x32_bf16 v[56:59], v[204:207], v[72:75], 0
	v_mfma_f32_16x16x32_bf16 v[52:55], v[212:215], v[72:75], 0
	v_mfma_f32_16x16x32_bf16 v[48:51], v[240:243], v[72:75], 0
	v_mfma_f32_16x16x32_bf16 v[56:59], v[208:211], v[8:11], v[56:59]
	v_mfma_f32_16x16x32_bf16 v[52:55], v[216:219], v[8:11], v[52:55]
	v_mfma_f32_16x16x32_bf16 v[48:51], v[244:247], v[8:11], v[48:51]
	ds_read_b128 v[204:207], v82 offset:13824
	ds_read_b128 v[208:211], v82 offset:13888
	ds_read_b128 v[212:215], v82 offset:16128
	ds_read_b128 v[216:219], v82 offset:16192
	ds_read_b128 v[240:243], v82 offset:18432
	ds_read_b128 v[244:247], v82 offset:18496
	s_waitcnt lgkmcnt(0)
	v_mfma_f32_16x16x32_bf16 v[44:47], v[204:207], v[72:75], 0
	v_mfma_f32_16x16x32_bf16 v[40:43], v[212:215], v[72:75], 0
	v_mfma_f32_16x16x32_bf16 v[36:39], v[240:243], v[72:75], 0
	v_mfma_f32_16x16x32_bf16 v[44:47], v[208:211], v[8:11], v[44:47]
	v_mfma_f32_16x16x32_bf16 v[40:43], v[216:219], v[8:11], v[40:43]
	v_mfma_f32_16x16x32_bf16 v[36:39], v[244:247], v[8:11], v[36:39]
	ds_read_b128 v[204:207], v82 offset:20736
	ds_read_b128 v[208:211], v82 offset:20800
	ds_read_b128 v[212:215], v82 offset:23040
	ds_read_b128 v[216:219], v82 offset:23104
	ds_read_b128 v[240:243], v82 offset:25344
	ds_read_b128 v[244:247], v82 offset:25408
	s_waitcnt lgkmcnt(0)
	v_mfma_f32_16x16x32_bf16 v[32:35], v[204:207], v[72:75], 0
	v_mfma_f32_16x16x32_bf16 v[28:31], v[212:215], v[72:75], 0
	v_mfma_f32_16x16x32_bf16 v[24:27], v[240:243], v[72:75], 0
	v_mfma_f32_16x16x32_bf16 v[32:35], v[208:211], v[8:11], v[32:35]
	v_mfma_f32_16x16x32_bf16 v[28:31], v[216:219], v[8:11], v[28:31]
	v_mfma_f32_16x16x32_bf16 v[24:27], v[244:247], v[8:11], v[24:27]
	ds_read_b128 v[204:207], v82 offset:27648
	ds_read_b128 v[208:211], v82 offset:27712
	ds_read_b128 v[212:215], v82 offset:29952
	ds_read_b128 v[216:219], v82 offset:30016
	ds_read_b128 v[240:243], v82 offset:32256
	ds_read_b128 v[244:247], v82 offset:32320
	s_waitcnt lgkmcnt(0)
	v_mfma_f32_16x16x32_bf16 v[20:23], v[204:207], v[72:75], 0
	v_mfma_f32_16x16x32_bf16 v[16:19], v[212:215], v[72:75], 0
	v_mfma_f32_16x16x32_bf16 v[12:15], v[240:243], v[72:75], 0
	v_mfma_f32_16x16x32_bf16 v[20:23], v[208:211], v[8:11], v[20:23]
	v_mfma_f32_16x16x32_bf16 v[16:19], v[216:219], v[8:11], v[16:19]
	v_mfma_f32_16x16x32_bf16 v[12:15], v[244:247], v[8:11], v[12:15]
	ds_read_b128 v[204:207], v82 offset:34560
	ds_read_b128 v[208:211], v82 offset:34624
	s_waitcnt lgkmcnt(0)
	v_mfma_f32_16x16x32_bf16 v[212:215], v[204:207], v[72:75], 0
	v_mfma_f32_16x16x32_bf16 v[8:11], v[208:211], v[8:11], v[212:215]
	s_nop 4
	v_mul_f32_e32 v72, 0x3e000000, v68
	v_mul_f32_e32 v73, 0x3e000000, v69
	s_mov_b32 s2, 0xff61b1e6
	v_max3_f32 v72, v72, s2, v73
	v_mul_f32_e32 v73, 0x3e000000, v70
	v_mul_f32_e32 v74, 0x3e000000, v71
	v_max3_f32 v72, v72, v73, v74
	v_mul_f32_e32 v73, 0x3e000000, v64
	v_mul_f32_e32 v74, 0x3e000000, v65
	v_max3_f32 v72, v72, v73, v74
	v_mul_f32_e32 v73, 0x3e000000, v66
	v_mul_f32_e32 v74, 0x3e000000, v67
	v_max3_f32 v72, v72, v73, v74
	v_mul_f32_e32 v73, 0x3e000000, v60
	v_mul_f32_e32 v74, 0x3e000000, v61
	v_max3_f32 v72, v72, v73, v74
	v_mul_f32_e32 v73, 0x3e000000, v62
	v_mul_f32_e32 v74, 0x3e000000, v63
	v_max3_f32 v72, v72, v73, v74
	v_mul_f32_e32 v73, 0x3e000000, v56
	v_mul_f32_e32 v74, 0x3e000000, v57
	v_max3_f32 v72, v72, v73, v74
	v_mul_f32_e32 v73, 0x3e000000, v58
	v_mul_f32_e32 v74, 0x3e000000, v59
	v_max3_f32 v72, v72, v73, v74
	v_mul_f32_e32 v73, 0x3e000000, v52
	v_mul_f32_e32 v74, 0x3e000000, v53
	v_max3_f32 v72, v72, v73, v74
	v_mul_f32_e32 v73, 0x3e000000, v54
	v_mul_f32_e32 v74, 0x3e000000, v55
	v_max3_f32 v72, v72, v73, v74
	v_mul_f32_e32 v73, 0x3e000000, v48
	v_mul_f32_e32 v74, 0x3e000000, v49
	v_max3_f32 v72, v72, v73, v74
	v_mul_f32_e32 v73, 0x3e000000, v50
	v_mul_f32_e32 v74, 0x3e000000, v51
	v_max3_f32 v72, v72, v73, v74
	v_mul_f32_e32 v73, 0x3e000000, v44
	v_mul_f32_e32 v74, 0x3e000000, v45
	v_max3_f32 v72, v72, v73, v74
	v_mul_f32_e32 v73, 0x3e000000, v46
	v_mul_f32_e32 v74, 0x3e000000, v47
	v_max3_f32 v72, v72, v73, v74
	v_mul_f32_e32 v73, 0x3e000000, v40
	v_mul_f32_e32 v74, 0x3e000000, v41
	v_max3_f32 v72, v72, v73, v74
	v_mul_f32_e32 v73, 0x3e000000, v42
	v_mul_f32_e32 v74, 0x3e000000, v43
	v_max3_f32 v72, v72, v73, v74
	v_mul_f32_e32 v73, 0x3e000000, v36
	v_mul_f32_e32 v74, 0x3e000000, v37
	v_max3_f32 v72, v72, v73, v74
	v_mul_f32_e32 v73, 0x3e000000, v38
	v_mul_f32_e32 v74, 0x3e000000, v39
	v_max3_f32 v72, v72, v73, v74
	v_mul_f32_e32 v73, 0x3e000000, v32
	v_mul_f32_e32 v74, 0x3e000000, v33
	v_max3_f32 v72, v72, v73, v74
	v_mul_f32_e32 v73, 0x3e000000, v34
	v_mul_f32_e32 v74, 0x3e000000, v35
	v_max3_f32 v72, v72, v73, v74
	v_mul_f32_e32 v73, 0x3e000000, v28
	v_mul_f32_e32 v74, 0x3e000000, v29
	v_max3_f32 v72, v72, v73, v74
	v_mul_f32_e32 v73, 0x3e000000, v30
	v_mul_f32_e32 v74, 0x3e000000, v31
	v_max3_f32 v72, v72, v73, v74
	v_mul_f32_e32 v73, 0x3e000000, v24
	v_mul_f32_e32 v74, 0x3e000000, v25
	v_max3_f32 v72, v72, v73, v74
	v_mul_f32_e32 v73, 0x3e000000, v26
	v_mul_f32_e32 v74, 0x3e000000, v27
	v_max3_f32 v72, v72, v73, v74
	v_mul_f32_e32 v73, 0x3e000000, v20
	v_mul_f32_e32 v74, 0x3e000000, v21
	v_max3_f32 v72, v72, v73, v74
	v_mul_f32_e32 v73, 0x3e000000, v22
	v_mul_f32_e32 v74, 0x3e000000, v23
	v_max3_f32 v72, v72, v73, v74
	v_mul_f32_e32 v73, 0x3e000000, v16
	v_mul_f32_e32 v74, 0x3e000000, v17
	v_max3_f32 v72, v72, v73, v74
	v_mul_f32_e32 v73, 0x3e000000, v18
	v_mul_f32_e32 v74, 0x3e000000, v19
	v_max3_f32 v72, v72, v73, v74
	v_mul_f32_e32 v73, 0x3e000000, v12
	v_mul_f32_e32 v74, 0x3e000000, v13
	v_max3_f32 v72, v72, v73, v74
	v_mul_f32_e32 v73, 0x3e000000, v14
	v_mul_f32_e32 v74, 0x3e000000, v15
	v_max3_f32 v72, v72, v73, v74
	v_mul_f32_e32 v73, 0x3e000000, v8
	v_mul_f32_e32 v74, 0x3e000000, v9
	v_max3_f32 v72, v72, v73, v74
	v_mul_f32_e32 v73, 0x3e000000, v10
	v_mul_f32_e32 v74, 0x3e000000, v11
	v_max3_f32 v72, v72, v73, v74
	ds_bpermute_b32 v73, v83, v72
	s_mov_b32 s2, 0x3e000000
	s_waitcnt lgkmcnt(0)
	v_max_f32_e32 v73, v73, v73
	v_max_f32_e32 v72, v72, v73
	ds_bpermute_b32 v73, v84, v72
	s_waitcnt lgkmcnt(0)
	v_max_f32_e32 v73, v73, v73
	v_max_f32_e32 v86, v72, v73
	v_fma_f32 v68, v68, s2, -v86
	v_fma_f32 v69, v69, s2, -v86
	v_mul_f32_e32 v68, 0x3fb8aa3b, v68
	v_mul_f32_e32 v69, 0x3fb8aa3b, v69
	v_exp_f32_e32 v68, v68
	v_exp_f32_e32 v72, v69
	v_fma_f32 v69, v70, s2, -v86
	v_mul_f32_e32 v69, 0x3fb8aa3b, v69
	v_fma_f32 v70, v71, s2, -v86
	v_exp_f32_e32 v69, v69
	v_mul_f32_e32 v70, 0x3fb8aa3b, v70
	v_exp_f32_e32 v73, v70
	v_add_f32_e32 v70, 0, v68
	v_add_f32_e32 v70, v72, v70
	v_fma_f32 v64, v64, s2, -v86
	v_add_f32_e32 v70, v69, v70
	v_mul_f32_e32 v64, 0x3fb8aa3b, v64
	v_add_f32_e32 v87, v73, v70
	v_exp_f32_e32 v70, v64
	v_fma_f32 v64, v65, s2, -v86
	v_mul_f32_e32 v64, 0x3fb8aa3b, v64
	v_exp_f32_e32 v74, v64
	v_fma_f32 v64, v66, s2, -v86
	v_mul_f32_e32 v64, 0x3fb8aa3b, v64
	v_exp_f32_e32 v71, v64
	v_fma_f32 v64, v67, s2, -v86
	v_mul_f32_e32 v64, 0x3fb8aa3b, v64
	v_exp_f32_e32 v75, v64
	v_add_f32_e32 v64, v70, v87
	v_add_f32_e32 v64, v74, v64
	v_fma_f32 v60, v60, s2, -v86
	v_fma_f32 v61, v61, s2, -v86
	v_add_f32_e32 v64, v71, v64
	v_mul_f32_e32 v60, 0x3fb8aa3b, v60
	v_mul_f32_e32 v61, 0x3fb8aa3b, v61
	v_add_f32_e32 v66, v75, v64
	v_exp_f32_e32 v60, v60
	v_exp_f32_e32 v64, v61
	v_fma_f32 v61, v62, s2, -v86
	v_mul_f32_e32 v61, 0x3fb8aa3b, v61
	v_fma_f32 v62, v63, s2, -v86
	v_exp_f32_e32 v61, v61
	v_mul_f32_e32 v62, 0x3fb8aa3b, v62
	v_exp_f32_e32 v65, v62
	v_add_f32_e32 v62, v60, v66
	v_add_f32_e32 v62, v64, v62
	v_fma_f32 v56, v56, s2, -v86
	v_add_f32_e32 v62, v61, v62
	v_mul_f32_e32 v56, 0x3fb8aa3b, v56
	v_add_f32_e32 v87, v65, v62
	v_exp_f32_e32 v62, v56
	v_fma_f32 v56, v57, s2, -v86
	v_mul_f32_e32 v56, 0x3fb8aa3b, v56
	v_exp_f32_e32 v66, v56
	v_fma_f32 v56, v58, s2, -v86
	v_mul_f32_e32 v56, 0x3fb8aa3b, v56
	v_exp_f32_e32 v63, v56
	v_fma_f32 v56, v59, s2, -v86
	v_mul_f32_e32 v56, 0x3fb8aa3b, v56
	v_exp_f32_e32 v67, v56
	v_add_f32_e32 v56, v62, v87
	v_add_f32_e32 v56, v66, v56
	v_fma_f32 v52, v52, s2, -v86
	v_fma_f32 v53, v53, s2, -v86
	v_add_f32_e32 v56, v63, v56
	v_mul_f32_e32 v52, 0x3fb8aa3b, v52
	v_mul_f32_e32 v53, 0x3fb8aa3b, v53
	v_add_f32_e32 v58, v67, v56
	v_exp_f32_e32 v52, v52
	v_exp_f32_e32 v56, v53
	v_fma_f32 v53, v54, s2, -v86
	v_mul_f32_e32 v53, 0x3fb8aa3b, v53
	v_fma_f32 v54, v55, s2, -v86
	v_exp_f32_e32 v53, v53
	v_mul_f32_e32 v54, 0x3fb8aa3b, v54
	v_exp_f32_e32 v57, v54
	v_add_f32_e32 v54, v52, v58
	v_add_f32_e32 v54, v56, v54
	v_fma_f32 v48, v48, s2, -v86
	v_add_f32_e32 v54, v53, v54
	v_mul_f32_e32 v48, 0x3fb8aa3b, v48
	v_add_f32_e32 v87, v57, v54
	v_exp_f32_e32 v54, v48
	v_fma_f32 v48, v49, s2, -v86
	v_mul_f32_e32 v48, 0x3fb8aa3b, v48
	v_exp_f32_e32 v58, v48
	v_fma_f32 v48, v50, s2, -v86
	v_mul_f32_e32 v48, 0x3fb8aa3b, v48
	v_exp_f32_e32 v55, v48
	v_fma_f32 v48, v51, s2, -v86
	v_mul_f32_e32 v48, 0x3fb8aa3b, v48
	v_exp_f32_e32 v59, v48
	v_add_f32_e32 v48, v54, v87
	v_add_f32_e32 v48, v58, v48
	v_fma_f32 v44, v44, s2, -v86
	v_fma_f32 v45, v45, s2, -v86
	v_add_f32_e32 v48, v55, v48
	v_mul_f32_e32 v44, 0x3fb8aa3b, v44
	v_mul_f32_e32 v45, 0x3fb8aa3b, v45
	v_add_f32_e32 v50, v59, v48
	v_exp_f32_e32 v44, v44
	v_exp_f32_e32 v48, v45
	v_fma_f32 v45, v46, s2, -v86
	v_mul_f32_e32 v45, 0x3fb8aa3b, v45
	v_fma_f32 v46, v47, s2, -v86
	v_exp_f32_e32 v45, v45
	v_mul_f32_e32 v46, 0x3fb8aa3b, v46
	v_exp_f32_e32 v49, v46
	v_add_f32_e32 v46, v44, v50
	v_add_f32_e32 v46, v48, v46
	v_fma_f32 v40, v40, s2, -v86
	v_add_f32_e32 v46, v45, v46
	v_mul_f32_e32 v40, 0x3fb8aa3b, v40
	v_add_f32_e32 v87, v49, v46
	v_exp_f32_e32 v46, v40
	v_fma_f32 v40, v41, s2, -v86
	v_mul_f32_e32 v40, 0x3fb8aa3b, v40
	v_exp_f32_e32 v50, v40
	v_fma_f32 v40, v42, s2, -v86
	v_mul_f32_e32 v40, 0x3fb8aa3b, v40
	v_exp_f32_e32 v47, v40
	v_fma_f32 v40, v43, s2, -v86
	v_mul_f32_e32 v40, 0x3fb8aa3b, v40
	v_exp_f32_e32 v51, v40
	v_add_f32_e32 v40, v46, v87
	v_add_f32_e32 v40, v50, v40
	v_fma_f32 v36, v36, s2, -v86
	v_fma_f32 v37, v37, s2, -v86
	v_add_f32_e32 v40, v47, v40
	v_mul_f32_e32 v36, 0x3fb8aa3b, v36
	v_mul_f32_e32 v37, 0x3fb8aa3b, v37
	v_add_f32_e32 v42, v51, v40
	v_exp_f32_e32 v36, v36
	v_exp_f32_e32 v40, v37
	v_fma_f32 v37, v38, s2, -v86
	v_mul_f32_e32 v37, 0x3fb8aa3b, v37
	v_fma_f32 v38, v39, s2, -v86
	v_exp_f32_e32 v37, v37
	v_mul_f32_e32 v38, 0x3fb8aa3b, v38
	v_exp_f32_e32 v41, v38
	v_add_f32_e32 v38, v36, v42
	v_add_f32_e32 v38, v40, v38
	v_fma_f32 v32, v32, s2, -v86
	v_add_f32_e32 v38, v37, v38
	v_mul_f32_e32 v32, 0x3fb8aa3b, v32
	v_add_f32_e32 v87, v41, v38
	v_exp_f32_e32 v38, v32
	v_fma_f32 v32, v33, s2, -v86
	v_mul_f32_e32 v32, 0x3fb8aa3b, v32
	v_exp_f32_e32 v42, v32
	v_fma_f32 v32, v34, s2, -v86
	v_mul_f32_e32 v32, 0x3fb8aa3b, v32
	v_exp_f32_e32 v39, v32
	v_fma_f32 v32, v35, s2, -v86
	v_mul_f32_e32 v32, 0x3fb8aa3b, v32
	v_exp_f32_e32 v43, v32
	v_add_f32_e32 v32, v38, v87
	v_add_f32_e32 v32, v42, v32
	v_fma_f32 v28, v28, s2, -v86
	v_fma_f32 v29, v29, s2, -v86
	v_add_f32_e32 v32, v39, v32
	v_mul_f32_e32 v28, 0x3fb8aa3b, v28
	v_mul_f32_e32 v29, 0x3fb8aa3b, v29
	v_add_f32_e32 v34, v43, v32
	v_exp_f32_e32 v28, v28
	v_exp_f32_e32 v32, v29
	v_fma_f32 v29, v30, s2, -v86
	v_mul_f32_e32 v29, 0x3fb8aa3b, v29
	v_fma_f32 v30, v31, s2, -v86
	v_exp_f32_e32 v29, v29
	v_mul_f32_e32 v30, 0x3fb8aa3b, v30
	v_exp_f32_e32 v33, v30
	v_add_f32_e32 v30, v28, v34
	v_add_f32_e32 v30, v32, v30
	v_fma_f32 v24, v24, s2, -v86
	v_add_f32_e32 v30, v29, v30
	v_mul_f32_e32 v24, 0x3fb8aa3b, v24
	v_add_f32_e32 v87, v33, v30
	v_exp_f32_e32 v30, v24
	v_fma_f32 v24, v25, s2, -v86
	v_mul_f32_e32 v24, 0x3fb8aa3b, v24
	v_exp_f32_e32 v34, v24
	v_fma_f32 v24, v26, s2, -v86
	v_mul_f32_e32 v24, 0x3fb8aa3b, v24
	v_exp_f32_e32 v31, v24
	v_fma_f32 v24, v27, s2, -v86
	v_mul_f32_e32 v24, 0x3fb8aa3b, v24
	v_exp_f32_e32 v35, v24
	v_add_f32_e32 v24, v30, v87
	v_add_f32_e32 v24, v34, v24
	v_fma_f32 v20, v20, s2, -v86
	v_fma_f32 v21, v21, s2, -v86
	v_add_f32_e32 v24, v31, v24
	v_mul_f32_e32 v20, 0x3fb8aa3b, v20
	v_mul_f32_e32 v21, 0x3fb8aa3b, v21
	v_add_f32_e32 v26, v35, v24
	v_exp_f32_e32 v20, v20
	v_exp_f32_e32 v24, v21
	v_fma_f32 v21, v22, s2, -v86
	v_mul_f32_e32 v21, 0x3fb8aa3b, v21
	v_fma_f32 v22, v23, s2, -v86
	v_exp_f32_e32 v21, v21
	v_mul_f32_e32 v22, 0x3fb8aa3b, v22
	v_exp_f32_e32 v25, v22
	v_add_f32_e32 v22, v20, v26
	v_add_f32_e32 v22, v24, v22
	v_fma_f32 v16, v16, s2, -v86
	v_add_f32_e32 v22, v21, v22
	v_mul_f32_e32 v16, 0x3fb8aa3b, v16
	v_add_f32_e32 v87, v25, v22
	v_exp_f32_e32 v22, v16
	v_fma_f32 v16, v17, s2, -v86
	v_mul_f32_e32 v16, 0x3fb8aa3b, v16
	v_exp_f32_e32 v26, v16
	v_fma_f32 v16, v18, s2, -v86
	v_mul_f32_e32 v16, 0x3fb8aa3b, v16
	v_exp_f32_e32 v23, v16
	v_fma_f32 v16, v19, s2, -v86
	v_mul_f32_e32 v16, 0x3fb8aa3b, v16
	v_exp_f32_e32 v27, v16
	v_add_f32_e32 v16, v22, v87
	v_add_f32_e32 v16, v26, v16
	v_fma_f32 v12, v12, s2, -v86
	v_fma_f32 v13, v13, s2, -v86
	v_add_f32_e32 v16, v23, v16
	v_mul_f32_e32 v12, 0x3fb8aa3b, v12
	v_mul_f32_e32 v13, 0x3fb8aa3b, v13
	v_add_f32_e32 v18, v27, v16
	v_exp_f32_e32 v12, v12
	v_exp_f32_e32 v16, v13
	v_fma_f32 v13, v14, s2, -v86
	v_mul_f32_e32 v13, 0x3fb8aa3b, v13
	v_fma_f32 v14, v15, s2, -v86
	v_exp_f32_e32 v13, v13
	v_mul_f32_e32 v14, 0x3fb8aa3b, v14
	v_exp_f32_e32 v17, v14
	v_add_f32_e32 v14, v12, v18
	v_add_f32_e32 v14, v16, v14
	v_fma_f32 v8, v8, s2, -v86
	v_fma_f32 v9, v9, s2, -v86
	v_add_f32_e32 v14, v13, v14
	v_mul_f32_e32 v8, 0x3fb8aa3b, v8
	v_mul_f32_e32 v9, 0x3fb8aa3b, v9
	v_add_f32_e32 v18, v17, v14
	v_exp_f32_e32 v8, v8
	v_exp_f32_e32 v14, v9
	v_fma_f32 v9, v10, s2, -v86
	v_mul_f32_e32 v9, 0x3fb8aa3b, v9
	v_fma_f32 v10, v11, s2, -v86
	v_exp_f32_e32 v9, v9
	v_mul_f32_e32 v10, 0x3fb8aa3b, v10
	v_exp_f32_e32 v15, v10
	v_add_f32_e32 v10, v8, v18
	v_add_f32_e32 v10, v14, v10
	v_add_f32_e32 v10, v9, v10
	v_add_f32_e32 v10, v15, v10
	ds_bpermute_b32 v11, v83, v10
	s_waitcnt lgkmcnt(0)
	v_add_f32_e32 v10, v10, v11
	ds_bpermute_b32 v11, v84, v10
	s_waitcnt lgkmcnt(0)
	v_add_f32_e32 v10, v10, v11
	v_div_scale_f32 v11, s[2:3], v10, v10, 1.0
	v_rcp_f32_e32 v18, v11
	v_div_scale_f32 v19, vcc, 1.0, v10, 1.0
	v_fma_f32 v86, -v11, v18, 1.0
	v_fmac_f32_e32 v18, v86, v18
	v_mul_f32_e32 v86, v19, v18
	v_fma_f32 v87, -v11, v86, v19
	v_fmac_f32_e32 v86, v87, v18
	v_fma_f32 v11, -v11, v86, v19
	v_div_fmas_f32 v11, v11, v18, v86
	v_div_fixup_f32 v10, v11, v10, 1.0
	v_pk_mul_f32 v[18:19], v[68:69], v[10:11] op_sel_hi:[1,0]
	v_pk_mul_f32 v[68:69], v[72:73], v[10:11] op_sel_hi:[1,0]
	v_pk_mul_f32 v[72:73], v[74:75], v[10:11] op_sel_hi:[1,0]
	v_pk_mul_f32 v[70:71], v[70:71], v[10:11] op_sel_hi:[1,0]
	v_bfe_u32 v11, v73, 16, 1
	v_bfe_u32 v74, v72, 16, 1
	v_bfe_u32 v75, v69, 16, 1
	v_bfe_u32 v86, v68, 16, 1
	v_add3_u32 v73, v73, v11, s33
	v_bfe_u32 v11, v18, 16, 1
	v_add3_u32 v86, v68, v86, s33
	v_add3_u32 v87, v69, v75, s33
	v_add3_u32 v72, v72, v74, s33
	v_bfe_u32 v68, v19, 16, 1
	v_bfe_u32 v69, v70, 16, 1
	v_bfe_u32 v74, v71, 16, 1
	v_add3_u32 v18, v18, v11, s33
	v_add_u32_e32 v11, 0x9000, v85
	v_add3_u32 v74, v71, v74, s33
	v_add3_u32 v75, v70, v69, s33
	v_add3_u32 v19, v19, v68, s33
	ds_read2_b64 v[68:71], v11 offset1:4
	v_lshrrev_b32_e32 v18, 16, v18
	v_lshrrev_b32_e32 v19, 16, v19
	v_lshrrev_b32_e32 v88, 16, v75
	v_lshrrev_b32_e32 v74, 16, v74
	v_and_or_b32 v75, v73, s29, v74
	v_and_or_b32 v74, v72, s29, v88
	v_and_or_b32 v73, v87, s29, v19
	v_and_or_b32 v72, v86, s29, v18
	v_add_u32_e32 v18, 0xb000, v85
	s_waitcnt lgkmcnt(0)
	v_mfma_f32_16x16x32_bf16 v[86:89], v[68:71], v[72:75], 0
	ds_read2_b64 v[68:71], v18 offset0:32 offset1:36
	s_waitcnt lgkmcnt(0)
	v_mfma_f32_16x16x32_bf16 v[90:93], v[68:71], v[72:75], 0
	v_add_u32_e32 v68, 0xd000, v85
	v_add_u32_e32 v69, 0xf000, v85
	ds_read2_b64 v[94:97], v68 offset0:64 offset1:68
	ds_read2_b64 v[98:101], v69 offset0:96 offset1:100
	s_waitcnt lgkmcnt(1)
	v_mfma_f32_16x16x32_bf16 v[94:97], v[94:97], v[72:75], 0
	s_waitcnt lgkmcnt(0)
	v_mfma_f32_16x16x32_bf16 v[70:73], v[98:101], v[72:75], 0
	v_mul_f32_e64 v64, v64, v10
	v_mul_f32_e64 v65, v65, v10
	v_pk_mul_f32 v[66:67], v[66:67], v[10:11] op_sel_hi:[1,0]
	v_pk_mul_f32 v[60:61], v[60:61], v[10:11] op_sel_hi:[1,0]
	v_pk_mul_f32 v[62:63], v[62:63], v[10:11] op_sel_hi:[1,0]
	v_bfe_u32 v19, v67, 16, 1
	v_bfe_u32 v74, v66, 16, 1
	v_bfe_u32 v75, v65, 16, 1
	v_bfe_u32 v98, v64, 16, 1
	v_add3_u32 v64, v64, v98, s33
	v_add3_u32 v65, v65, v75, s33
	v_add3_u32 v66, v66, v74, s33
	v_add3_u32 v19, v67, v19, s33
	v_bfe_u32 v67, v60, 16, 1
	v_bfe_u32 v74, v61, 16, 1
	v_bfe_u32 v75, v62, 16, 1
	v_bfe_u32 v98, v63, 16, 1
	v_add3_u32 v98, v63, v98, s33
	v_add3_u32 v75, v62, v75, s33
	v_add3_u32 v74, v61, v74, s33
	v_add3_u32 v67, v60, v67, s33
	ds_read2_b64 v[60:63], v11 offset0:8 offset1:12
	v_lshrrev_b32_e32 v99, 16, v67
	v_lshrrev_b32_e32 v74, 16, v74
	v_lshrrev_b32_e32 v75, 16, v75
	v_lshrrev_b32_e32 v67, 16, v98
	v_and_or_b32 v67, v19, s29, v67
	v_and_or_b32 v66, v66, s29, v75
	v_and_or_b32 v65, v65, s29, v74
	v_and_or_b32 v64, v64, s29, v99
	s_waitcnt lgkmcnt(0)
	s_nop 0
	v_mfma_f32_16x16x32_bf16 v[60:63], v[60:63], v[64:67], v[86:89]
	s_nop 2
	ds_read2_b64 v[86:89], v18 offset0:40 offset1:44
	s_waitcnt lgkmcnt(0)
	v_mfma_f32_16x16x32_bf16 v[86:89], v[86:89], v[64:67], v[90:93]
	s_nop 2
	ds_read2_b64 v[90:93], v68 offset0:72 offset1:76
	s_waitcnt lgkmcnt(0)
	v_mfma_f32_16x16x32_bf16 v[90:93], v[90:93], v[64:67], v[94:97]
	s_nop 2
	ds_read2_b64 v[94:97], v69 offset0:104 offset1:108
	s_waitcnt lgkmcnt(0)
	v_mfma_f32_16x16x32_bf16 v[64:67], v[94:97], v[64:67], v[70:73]
	v_mul_f32_e64 v56, v56, v10
	v_mul_f32_e64 v57, v57, v10
	v_pk_mul_f32 v[58:59], v[58:59], v[10:11] op_sel_hi:[1,0]
	v_pk_mul_f32 v[52:53], v[52:53], v[10:11] op_sel_hi:[1,0]
	v_pk_mul_f32 v[54:55], v[54:55], v[10:11] op_sel_hi:[1,0]
	v_bfe_u32 v19, v59, 16, 1
	v_bfe_u32 v70, v58, 16, 1
	v_bfe_u32 v71, v57, 16, 1
	v_bfe_u32 v72, v56, 16, 1
	v_add3_u32 v56, v56, v72, s33
	v_add3_u32 v57, v57, v71, s33
	v_add3_u32 v58, v58, v70, s33
	v_add3_u32 v19, v59, v19, s33
	v_bfe_u32 v59, v52, 16, 1
	v_bfe_u32 v70, v53, 16, 1
	v_bfe_u32 v71, v54, 16, 1
	v_bfe_u32 v72, v55, 16, 1
	v_add3_u32 v72, v55, v72, s33
	v_add3_u32 v71, v54, v71, s33
	v_add3_u32 v70, v53, v70, s33
	v_add3_u32 v59, v52, v59, s33
	ds_read2_b64 v[52:55], v11 offset0:16 offset1:20
	v_lshrrev_b32_e32 v73, 16, v59
	v_lshrrev_b32_e32 v70, 16, v70
	v_lshrrev_b32_e32 v71, 16, v71
	v_lshrrev_b32_e32 v59, 16, v72
	v_and_or_b32 v59, v19, s29, v59
	v_and_or_b32 v58, v58, s29, v71
	v_and_or_b32 v57, v57, s29, v70
	v_and_or_b32 v56, v56, s29, v73
	ds_read2_b64 v[70:73], v68 offset0:80 offset1:84
	s_waitcnt lgkmcnt(1)
	v_mfma_f32_16x16x32_bf16 v[52:55], v[52:55], v[56:59], v[60:63]
	s_nop 2
	ds_read2_b64 v[60:63], v18 offset0:48 offset1:52
	s_waitcnt lgkmcnt(0)
	v_mfma_f32_16x16x32_bf16 v[60:63], v[60:63], v[56:59], v[86:89]
	s_nop 2
	ds_read2_b64 v[86:89], v69 offset0:112 offset1:116
	v_mfma_f32_16x16x32_bf16 v[70:73], v[70:73], v[56:59], v[90:93]
	s_waitcnt lgkmcnt(0)
	v_mfma_f32_16x16x32_bf16 v[56:59], v[86:89], v[56:59], v[64:67]
	v_mul_f32_e64 v48, v48, v10
	v_mul_f32_e64 v49, v49, v10
	v_pk_mul_f32 v[50:51], v[50:51], v[10:11] op_sel_hi:[1,0]
	v_pk_mul_f32 v[44:45], v[44:45], v[10:11] op_sel_hi:[1,0]
	v_pk_mul_f32 v[46:47], v[46:47], v[10:11] op_sel_hi:[1,0]
	v_bfe_u32 v19, v51, 16, 1
	v_bfe_u32 v64, v50, 16, 1
	v_bfe_u32 v65, v49, 16, 1
	v_bfe_u32 v66, v48, 16, 1
	v_add3_u32 v48, v48, v66, s33
	v_add3_u32 v49, v49, v65, s33
	v_add3_u32 v50, v50, v64, s33
	v_add3_u32 v19, v51, v19, s33
	v_bfe_u32 v51, v44, 16, 1
	v_bfe_u32 v64, v45, 16, 1
	v_bfe_u32 v65, v46, 16, 1
	v_bfe_u32 v66, v47, 16, 1
	v_add3_u32 v66, v47, v66, s33
	v_add3_u32 v65, v46, v65, s33
	v_add3_u32 v64, v45, v64, s33
	v_add3_u32 v51, v44, v51, s33
	ds_read2_b64 v[44:47], v11 offset0:24 offset1:28
	v_lshrrev_b32_e32 v67, 16, v51
	v_lshrrev_b32_e32 v64, 16, v64
	v_lshrrev_b32_e32 v65, 16, v65
	v_lshrrev_b32_e32 v51, 16, v66
	v_and_or_b32 v51, v19, s29, v51
	v_and_or_b32 v50, v50, s29, v65
	v_and_or_b32 v49, v49, s29, v64
	v_and_or_b32 v48, v48, s29, v67
	ds_read2_b64 v[64:67], v69 offset0:120 offset1:124
	s_waitcnt lgkmcnt(1)
	v_mfma_f32_16x16x32_bf16 v[44:47], v[44:47], v[48:51], v[52:55]
	s_nop 2
	ds_read2_b64 v[52:55], v18 offset0:56 offset1:60
	s_waitcnt lgkmcnt(0)
	v_mfma_f32_16x16x32_bf16 v[52:55], v[52:55], v[48:51], v[60:63]
	s_nop 2
	ds_read2_b64 v[60:63], v68 offset0:88 offset1:92
	s_waitcnt lgkmcnt(0)
	v_mfma_f32_16x16x32_bf16 v[60:63], v[60:63], v[48:51], v[70:73]
	v_mfma_f32_16x16x32_bf16 v[48:51], v[64:67], v[48:51], v[56:59]
	v_mul_f32_e64 v40, v40, v10
	v_mul_f32_e64 v41, v41, v10
	v_pk_mul_f32 v[42:43], v[42:43], v[10:11] op_sel_hi:[1,0]
	v_pk_mul_f32 v[36:37], v[36:37], v[10:11] op_sel_hi:[1,0]
	v_pk_mul_f32 v[38:39], v[38:39], v[10:11] op_sel_hi:[1,0]
	v_bfe_u32 v19, v43, 16, 1
	v_bfe_u32 v56, v42, 16, 1
	v_bfe_u32 v57, v41, 16, 1
	v_bfe_u32 v58, v40, 16, 1
	v_add3_u32 v40, v40, v58, s33
	v_add3_u32 v41, v41, v57, s33
	v_add3_u32 v42, v42, v56, s33
	v_add3_u32 v19, v43, v19, s33
	v_bfe_u32 v43, v36, 16, 1
	v_bfe_u32 v56, v37, 16, 1
	v_bfe_u32 v57, v38, 16, 1
	v_bfe_u32 v58, v39, 16, 1
	v_add3_u32 v58, v39, v58, s33
	v_add3_u32 v57, v38, v57, s33
	v_add3_u32 v56, v37, v56, s33
	v_add3_u32 v43, v36, v43, s33
	ds_read2_b64 v[36:39], v11 offset0:32 offset1:36
	v_lshrrev_b32_e32 v59, 16, v43
	v_lshrrev_b32_e32 v56, 16, v56
	v_lshrrev_b32_e32 v57, 16, v57
	v_lshrrev_b32_e32 v43, 16, v58
	v_and_or_b32 v43, v19, s29, v43
	v_and_or_b32 v42, v42, s29, v57
	v_and_or_b32 v41, v41, s29, v56
	v_and_or_b32 v40, v40, s29, v59
	ds_read2_b64 v[56:59], v69 offset0:128 offset1:132
	s_waitcnt lgkmcnt(1)
	v_mfma_f32_16x16x32_bf16 v[36:39], v[36:39], v[40:43], v[44:47]
	s_nop 2
	ds_read2_b64 v[44:47], v18 offset0:64 offset1:68
	s_waitcnt lgkmcnt(0)
	v_mfma_f32_16x16x32_bf16 v[44:47], v[44:47], v[40:43], v[52:55]
	s_nop 2
	ds_read2_b64 v[52:55], v68 offset0:96 offset1:100
	s_waitcnt lgkmcnt(0)
	v_mfma_f32_16x16x32_bf16 v[52:55], v[52:55], v[40:43], v[60:63]
	v_mfma_f32_16x16x32_bf16 v[40:43], v[56:59], v[40:43], v[48:51]
	v_mul_f32_e64 v32, v32, v10
	v_mul_f32_e64 v33, v33, v10
	v_pk_mul_f32 v[34:35], v[34:35], v[10:11] op_sel_hi:[1,0]
	v_pk_mul_f32 v[28:29], v[28:29], v[10:11] op_sel_hi:[1,0]
	v_pk_mul_f32 v[30:31], v[30:31], v[10:11] op_sel_hi:[1,0]
	v_bfe_u32 v19, v35, 16, 1
	v_bfe_u32 v48, v34, 16, 1
	v_bfe_u32 v49, v33, 16, 1
	v_bfe_u32 v50, v32, 16, 1
	v_add3_u32 v32, v32, v50, s33
	v_add3_u32 v33, v33, v49, s33
	v_add3_u32 v34, v34, v48, s33
	v_add3_u32 v19, v35, v19, s33
	v_bfe_u32 v35, v28, 16, 1
	v_bfe_u32 v48, v29, 16, 1
	v_bfe_u32 v49, v30, 16, 1
	v_bfe_u32 v50, v31, 16, 1
	v_add3_u32 v50, v31, v50, s33
	v_add3_u32 v49, v30, v49, s33
	v_add3_u32 v48, v29, v48, s33
	v_add3_u32 v35, v28, v35, s33
	ds_read2_b64 v[28:31], v11 offset0:40 offset1:44
	v_lshrrev_b32_e32 v51, 16, v35
	v_lshrrev_b32_e32 v48, 16, v48
	v_lshrrev_b32_e32 v49, 16, v49
	v_lshrrev_b32_e32 v35, 16, v50
	v_and_or_b32 v35, v19, s29, v35
	v_and_or_b32 v34, v34, s29, v49
	v_and_or_b32 v33, v33, s29, v48
	v_and_or_b32 v32, v32, s29, v51
	ds_read2_b64 v[48:51], v69 offset0:136 offset1:140
	s_waitcnt lgkmcnt(1)
	v_mfma_f32_16x16x32_bf16 v[28:31], v[28:31], v[32:35], v[36:39]
	s_nop 2
	ds_read2_b64 v[36:39], v18 offset0:72 offset1:76
	s_waitcnt lgkmcnt(0)
	v_mfma_f32_16x16x32_bf16 v[36:39], v[36:39], v[32:35], v[44:47]
	s_nop 2
	ds_read2_b64 v[44:47], v68 offset0:104 offset1:108
	s_waitcnt lgkmcnt(0)
	v_mfma_f32_16x16x32_bf16 v[44:47], v[44:47], v[32:35], v[52:55]
	v_mfma_f32_16x16x32_bf16 v[32:35], v[48:51], v[32:35], v[40:43]
	v_mul_f32_e64 v24, v24, v10
	v_mul_f32_e64 v25, v25, v10
	v_pk_mul_f32 v[26:27], v[26:27], v[10:11] op_sel_hi:[1,0]
	v_pk_mul_f32 v[20:21], v[20:21], v[10:11] op_sel_hi:[1,0]
	v_pk_mul_f32 v[22:23], v[22:23], v[10:11] op_sel_hi:[1,0]
	v_bfe_u32 v19, v27, 16, 1
	v_bfe_u32 v40, v26, 16, 1
	v_bfe_u32 v41, v25, 16, 1
	v_bfe_u32 v42, v24, 16, 1
	v_add3_u32 v24, v24, v42, s33
	v_add3_u32 v25, v25, v41, s33
	v_add3_u32 v26, v26, v40, s33
	v_add3_u32 v19, v27, v19, s33
	v_bfe_u32 v27, v20, 16, 1
	v_bfe_u32 v40, v21, 16, 1
	v_bfe_u32 v41, v22, 16, 1
	v_bfe_u32 v42, v23, 16, 1
	v_add3_u32 v42, v23, v42, s33
	v_add3_u32 v41, v22, v41, s33
	v_add3_u32 v40, v21, v40, s33
	v_add3_u32 v27, v20, v27, s33
	ds_read2_b64 v[20:23], v11 offset0:48 offset1:52
	v_lshrrev_b32_e32 v43, 16, v27
	v_lshrrev_b32_e32 v40, 16, v40
	v_lshrrev_b32_e32 v41, 16, v41
	v_lshrrev_b32_e32 v27, 16, v42
	v_and_or_b32 v27, v19, s29, v27
	v_and_or_b32 v26, v26, s29, v41
	v_and_or_b32 v25, v25, s29, v40
	v_and_or_b32 v24, v24, s29, v43
	ds_read2_b64 v[40:43], v69 offset0:144 offset1:148
	s_waitcnt lgkmcnt(1)
	v_mfma_f32_16x16x32_bf16 v[20:23], v[20:23], v[24:27], v[28:31]
	s_nop 2
	ds_read2_b64 v[28:31], v18 offset0:80 offset1:84
	s_waitcnt lgkmcnt(0)
	v_mfma_f32_16x16x32_bf16 v[28:31], v[28:31], v[24:27], v[36:39]
	s_nop 2
	ds_read2_b64 v[36:39], v68 offset0:112 offset1:116
	s_waitcnt lgkmcnt(0)
	v_mfma_f32_16x16x32_bf16 v[36:39], v[36:39], v[24:27], v[44:47]
	v_mfma_f32_16x16x32_bf16 v[24:27], v[40:43], v[24:27], v[32:35]
	v_mul_f32_e64 v16, v16, v10
	v_mul_f32_e64 v17, v17, v10
	v_pk_mul_f32 v[14:15], v[14:15], v[10:11] op_sel_hi:[1,0]
	v_pk_mul_f32 v[12:13], v[12:13], v[10:11] op_sel_hi:[1,0]
	v_pk_mul_f32 v[8:9], v[8:9], v[10:11] op_sel_hi:[1,0]
	v_bfe_u32 v10, v15, 16, 1
	v_bfe_u32 v32, v17, 16, 1
	v_bfe_u32 v33, v16, 16, 1
	v_add3_u32 v16, v16, v33, s33
	v_add3_u32 v17, v17, v32, s33
	v_add3_u32 v15, v15, v10, s33
	v_bfe_u32 v10, v12, 16, 1
	v_bfe_u32 v32, v8, 16, 1
	v_bfe_u32 v33, v9, 16, 1
	v_add3_u32 v33, v9, v33, s33
	v_add3_u32 v32, v8, v32, s33
	v_add3_u32 v12, v12, v10, s33
	ds_read2_b64 v[8:11], v11 offset0:56 offset1:60
	v_bfe_u32 v19, v14, 16, 1
	v_add3_u32 v14, v14, v19, s33
	v_bfe_u32 v19, v13, 16, 1
	v_add3_u32 v13, v13, v19, s33
	v_lshrrev_b32_e32 v12, 16, v12
	v_lshrrev_b32_e32 v13, 16, v13
	v_lshrrev_b32_e32 v19, 16, v32
	v_lshrrev_b32_e32 v32, 16, v33
	v_and_or_b32 v35, v15, s29, v32
	v_and_or_b32 v34, v14, s29, v19
	v_and_or_b32 v33, v17, s29, v13
	v_and_or_b32 v32, v16, s29, v12
	s_waitcnt lgkmcnt(0)
	s_nop 0
	v_mfma_f32_16x16x32_bf16 v[20:23], v[8:11], v[32:35], v[20:23]
	ds_read2_b64 v[8:11], v18 offset0:88 offset1:92
	s_waitcnt lgkmcnt(0)
	v_mfma_f32_16x16x32_bf16 v[16:19], v[8:11], v[32:35], v[28:31]
	ds_read2_b64 v[8:11], v68 offset0:120 offset1:124
	s_waitcnt lgkmcnt(0)
	v_mfma_f32_16x16x32_bf16 v[12:15], v[8:11], v[32:35], v[36:39]
	ds_read2_b64 v[8:11], v69 offset0:152 offset1:156
	s_waitcnt lgkmcnt(0)
	v_mfma_f32_16x16x32_bf16 v[8:11], v[8:11], v[32:35], v[24:27]
	s_and_saveexec_b64 s[2:3], s[0:1]
	s_cbranch_execz .LBB0_98
	s_nop 0
	v_bfe_u32 v26, v20, 16, 1
	v_add3_u32 v20, v20, v26, s33
	v_bfe_u32 v26, v21, 16, 1
	v_add3_u32 v21, v21, v26, s33
	v_lshrrev_b32_e32 v20, 16, v20
	v_add_u32_e32 v24, s6, v81
	v_and_or_b32 v20, v21, s29, v20
	v_bfe_u32 v21, v22, 16, 1
	v_ashrrev_i32_e32 v25, 31, v24
	v_add3_u32 v21, v22, v21, s33
	v_bfe_u32 v22, v23, 16, 1
	v_lshlrev_b64 v[24:25], 11, v[24:25]
	v_add3_u32 v22, v23, v22, s33
	v_lshrrev_b32_e32 v21, 16, v21
	v_lshl_add_u64 v[24:25], v[76:77], 0, v[24:25]
	v_and_or_b32 v21, v22, s29, v21
	global_store_dwordx2 v[24:25], v[20:21], off offset:1536
	v_bfe_u32 v20, v16, 16, 1
	v_add3_u32 v16, v16, v20, s33
	v_bfe_u32 v20, v17, 16, 1
	v_add3_u32 v17, v17, v20, s33
	v_lshrrev_b32_e32 v16, 16, v16
	v_and_or_b32 v16, v17, s29, v16
	v_bfe_u32 v17, v18, 16, 1
	v_add3_u32 v17, v18, v17, s33
	v_bfe_u32 v18, v19, 16, 1
	v_add3_u32 v18, v19, v18, s33
	v_lshrrev_b32_e32 v17, 16, v17
	v_and_or_b32 v17, v18, s29, v17
	global_store_dwordx2 v[24:25], v[16:17], off offset:1568
	v_bfe_u32 v16, v12, 16, 1
	v_add3_u32 v12, v12, v16, s33
	v_bfe_u32 v16, v13, 16, 1
	v_add3_u32 v13, v13, v16, s33
	v_lshrrev_b32_e32 v12, 16, v12
	v_and_or_b32 v12, v13, s29, v12
	v_bfe_u32 v13, v14, 16, 1
	v_add3_u32 v13, v14, v13, s33
	v_bfe_u32 v14, v15, 16, 1
	v_add3_u32 v14, v15, v14, s33
	v_lshrrev_b32_e32 v13, 16, v13
	v_and_or_b32 v13, v14, s29, v13
	global_store_dwordx2 v[24:25], v[12:13], off offset:1600
	v_bfe_u32 v12, v8, 16, 1
	v_add3_u32 v8, v8, v12, s33
	v_bfe_u32 v12, v9, 16, 1
	v_add3_u32 v9, v9, v12, s33
	v_lshrrev_b32_e32 v8, 16, v8
	v_and_or_b32 v8, v9, s29, v8
	v_bfe_u32 v9, v10, 16, 1
	v_add3_u32 v9, v10, v9, s33
	v_bfe_u32 v10, v11, 16, 1
	v_add3_u32 v10, v11, v10, s33
	v_lshrrev_b32_e32 v9, 16, v9
	v_and_or_b32 v9, v10, s29, v9
	global_store_dwordx2 v[24:25], v[8:9], off offset:1632
	s_branch .LBB0_98
